# v43 plus deletion of the already-satisfied s_waitcnt lgkmcnt(0) behind each pre-MMA barrier in the GEMM K loops
# speedup vs baseline: 1.0028x; 1.0028x over previous
.LBB0_307:
	s_add_u32 vcc_lo, s82, 0x80
	s_addc_u32 vcc_hi, s83, 0
	s_add_u32 s82, s42, 0x100
	s_addc_u32 s83, s43, 0
	s_mov_b32 s42, 0
	s_add_i32 s72, s42, 2
	s_add_u32 s73, vcc_lo, 0x80
	s_addc_u32 s43, vcc_hi, 0
	s_add_i32 s45, 0, 0x10000
	s_cmp_eq_u32 s63, s42
	s_cselect_b32 s43, s9, s43
	s_cselect_b32 s42, s8, s73
	v_add_u32_e32 v140, s45, v143
	s_cselect_b32 s75, s91, s83
	s_cselect_b32 s74, s90, s82
	s_add_i32 s73, 0, 0x14000
	ds_read_b128 v[146:149], v140
	ds_read_b128 v[150:153], v140 offset:1024
	ds_read_b128 v[154:157], v140 offset:2048
	ds_read_b128 v[158:161], v140 offset:3072
	v_add_u32_e32 v140, s73, v143
	ds_read_b128 v[162:165], v140
	ds_read_b128 v[166:169], v140 offset:1024
	ds_read_b128 v[170:173], v140 offset:2048
	ds_read_b128 v[174:177], v140 offset:3072
	v_lshl_add_u64 v[140:141], vcc, 0, v[136:137]
	s_add_i32 m0, s59, 0xc000
	ds_read_b128 v[178:181], v145
	ds_read_b128 v[182:185], v145 offset:1024
	ds_read_b128 v[186:189], v145 offset:2048
	ds_read_b128 v[190:193], v145 offset:3072
	ds_read_b128 v[202:205], v145 offset:4096
	ds_read_b128 v[206:209], v145 offset:5120
	ds_read_b128 v[220:223], v145 offset:6144
	ds_read_b128 v[224:227], v145 offset:7168
	global_load_lds_dwordx4 v[140:141], off
	v_lshl_add_u64 v[140:141], vcc, 0, v[138:139]
	s_add_i32 m0, s59, 0xe000
	s_nop 0
	global_load_lds_dwordx4 v[140:141], off
	s_waitcnt vmcnt(8)
	s_waitcnt lgkmcnt(0)
	s_barrier
	v_mfma_f32_16x16x32_bf16 v[126:129], v[146:149], v[178:181], 0
	v_mfma_f32_16x16x32_bf16 v[122:125], v[154:157], v[178:181], 0
	v_mfma_f32_16x16x32_bf16 v[118:121], v[146:149], v[186:189], 0
	v_mfma_f32_16x16x32_bf16 v[110:113], v[154:157], v[186:189], 0
	v_mfma_f32_16x16x32_bf16 v[102:105], v[146:149], v[202:205], 0
	v_mfma_f32_16x16x32_bf16 v[94:97], v[154:157], v[202:205], 0
	v_mfma_f32_16x16x32_bf16 v[86:89], v[146:149], v[220:223], 0
	v_mfma_f32_16x16x32_bf16 v[78:81], v[154:157], v[220:223], 0
	v_mfma_f32_16x16x32_bf16 v[126:129], v[150:153], v[182:185], v[126:129]
	v_mfma_f32_16x16x32_bf16 v[122:125], v[158:161], v[182:185], v[122:125]
	v_mfma_f32_16x16x32_bf16 v[118:121], v[150:153], v[190:193], v[118:121]
	v_mfma_f32_16x16x32_bf16 v[110:113], v[158:161], v[190:193], v[110:113]
	v_mfma_f32_16x16x32_bf16 v[102:105], v[150:153], v[206:209], v[102:105]
	v_mfma_f32_16x16x32_bf16 v[94:97], v[158:161], v[206:209], v[94:97]
	v_mfma_f32_16x16x32_bf16 v[86:89], v[150:153], v[224:227], v[86:89]
	v_mfma_f32_16x16x32_bf16 v[78:81], v[158:161], v[224:227], v[78:81]
	v_mfma_f32_16x16x32_bf16 v[114:117], v[162:165], v[178:181], 0
	v_mfma_f32_16x16x32_bf16 v[106:109], v[170:173], v[178:181], 0
	v_mfma_f32_16x16x32_bf16 v[98:101], v[162:165], v[186:189], 0
	v_mfma_f32_16x16x32_bf16 v[90:93], v[170:173], v[186:189], 0
	v_mfma_f32_16x16x32_bf16 v[82:85], v[162:165], v[202:205], 0
	v_mfma_f32_16x16x32_bf16 v[74:77], v[170:173], v[202:205], 0
	v_mfma_f32_16x16x32_bf16 v[70:73], v[162:165], v[220:223], 0
	v_mfma_f32_16x16x32_bf16 v[66:69], v[170:173], v[220:223], 0
	v_mfma_f32_16x16x32_bf16 v[114:117], v[166:169], v[182:185], v[114:117]
	v_mfma_f32_16x16x32_bf16 v[106:109], v[174:177], v[182:185], v[106:109]
	v_mfma_f32_16x16x32_bf16 v[98:101], v[166:169], v[190:193], v[98:101]
	v_mfma_f32_16x16x32_bf16 v[90:93], v[174:177], v[190:193], v[90:93]
	v_mfma_f32_16x16x32_bf16 v[82:85], v[166:169], v[206:209], v[82:85]
	v_mfma_f32_16x16x32_bf16 v[74:77], v[174:177], v[206:209], v[74:77]
	v_mfma_f32_16x16x32_bf16 v[70:73], v[166:169], v[224:227], v[70:73]
	v_mfma_f32_16x16x32_bf16 v[66:69], v[174:177], v[224:227], v[66:69]
	s_barrier
	s_add_i32 s45, s45, s54
	v_lshl_add_u64 v[140:141], s[74:75], 0, v[0:1]
	s_mov_b32 m0, s45
	ds_read_b128 v[178:181], v145 offset:16384
	ds_read_b128 v[182:185], v145 offset:17408
	ds_read_b128 v[186:189], v145 offset:18432
	ds_read_b128 v[190:193], v145 offset:19456
	ds_read_b128 v[202:205], v145 offset:20480
	ds_read_b128 v[206:209], v145 offset:21504
	ds_read_b128 v[220:223], v145 offset:22528
	ds_read_b128 v[224:227], v145 offset:23552
	global_load_lds_dwordx4 v[140:141], off
	s_add_i32 m0, s45, 0x2000
	v_lshl_add_u64 v[194:195], s[74:75], 0, v[134:135]
	s_add_u32 s74, s74, s80
	s_addc_u32 s75, s75, 0
	s_add_i32 s45, s73, s54
	global_load_lds_dwordx4 v[194:195], off
	v_lshl_add_u64 v[198:199], s[74:75], 0, v[0:1]
	s_mov_b32 m0, s45
	v_lshl_add_u64 v[200:201], s[74:75], 0, v[134:135]
	global_load_lds_dwordx4 v[198:199], off
	s_add_i32 m0, s45, 0x2000
	v_lshl_add_u64 v[210:211], s[42:43], 0, v[130:131]
	global_load_lds_dwordx4 v[200:201], off
	s_mov_b32 m0, s59
	v_lshl_add_u64 v[212:213], s[42:43], 0, v[132:133]
	global_load_lds_dwordx4 v[210:211], off
	s_mov_b32 m0, s60
	s_nop 0
	global_load_lds_dwordx4 v[212:213], off
	s_waitcnt vmcnt(8)
	s_waitcnt lgkmcnt(0)
	s_barrier
	v_mfma_f32_16x16x32_bf16 v[62:65], v[146:149], v[178:181], 0
	v_mfma_f32_16x16x32_bf16 v[58:61], v[154:157], v[178:181], 0
	v_mfma_f32_16x16x32_bf16 v[54:57], v[146:149], v[186:189], 0
	v_mfma_f32_16x16x32_bf16 v[46:49], v[154:157], v[186:189], 0
	v_mfma_f32_16x16x32_bf16 v[38:41], v[146:149], v[202:205], 0
	v_mfma_f32_16x16x32_bf16 v[30:33], v[154:157], v[202:205], 0
	v_mfma_f32_16x16x32_bf16 v[22:25], v[146:149], v[220:223], 0
	v_mfma_f32_16x16x32_bf16 v[14:17], v[154:157], v[220:223], 0
	v_mfma_f32_16x16x32_bf16 v[62:65], v[150:153], v[182:185], v[62:65]
	v_mfma_f32_16x16x32_bf16 v[58:61], v[158:161], v[182:185], v[58:61]
	v_mfma_f32_16x16x32_bf16 v[54:57], v[150:153], v[190:193], v[54:57]
	v_mfma_f32_16x16x32_bf16 v[46:49], v[158:161], v[190:193], v[46:49]
	v_mfma_f32_16x16x32_bf16 v[38:41], v[150:153], v[206:209], v[38:41]
	v_mfma_f32_16x16x32_bf16 v[30:33], v[158:161], v[206:209], v[30:33]
	v_mfma_f32_16x16x32_bf16 v[22:25], v[150:153], v[224:227], v[22:25]
	v_mfma_f32_16x16x32_bf16 v[14:17], v[158:161], v[224:227], v[14:17]
	v_mfma_f32_16x16x32_bf16 v[50:53], v[162:165], v[178:181], 0
	v_mfma_f32_16x16x32_bf16 v[42:45], v[170:173], v[178:181], 0
	v_mfma_f32_16x16x32_bf16 v[34:37], v[162:165], v[186:189], 0
	v_mfma_f32_16x16x32_bf16 v[26:29], v[170:173], v[186:189], 0
	v_mfma_f32_16x16x32_bf16 v[18:21], v[162:165], v[202:205], 0
	v_mfma_f32_16x16x32_bf16 v[10:13], v[170:173], v[202:205], 0
	v_mfma_f32_16x16x32_bf16 v[6:9], v[162:165], v[220:223], 0
	v_mfma_f32_16x16x32_bf16 v[2:5], v[170:173], v[220:223], 0
	v_mfma_f32_16x16x32_bf16 v[50:53], v[166:169], v[182:185], v[50:53]
	v_mfma_f32_16x16x32_bf16 v[42:45], v[174:177], v[182:185], v[42:45]
	v_mfma_f32_16x16x32_bf16 v[34:37], v[166:169], v[190:193], v[34:37]
	v_mfma_f32_16x16x32_bf16 v[26:29], v[174:177], v[190:193], v[26:29]
	v_mfma_f32_16x16x32_bf16 v[18:21], v[166:169], v[206:209], v[18:21]
	v_mfma_f32_16x16x32_bf16 v[10:13], v[174:177], v[206:209], v[10:13]
	v_mfma_f32_16x16x32_bf16 v[6:9], v[166:169], v[224:227], v[6:9]
	v_mfma_f32_16x16x32_bf16 v[2:5], v[174:177], v[224:227], v[2:5]
	s_barrier
	s_add_i32 s45, 0, 0x18000
	s_add_i32 s73, 0, 0x1c000
	v_add_u32_e32 v158, s45, v143
	v_add_u32_e32 v174, s73, v143
	ds_read_b128 v[146:149], v158
	ds_read_b128 v[150:153], v158 offset:1024
	ds_read_b128 v[154:157], v158 offset:2048
	ds_read_b128 v[158:161], v158 offset:3072
	ds_read_b128 v[162:165], v174
	ds_read_b128 v[166:169], v174 offset:1024
	ds_read_b128 v[170:173], v174 offset:2048
	ds_read_b128 v[174:177], v174 offset:3072
	s_add_u32 s42, s42, s80
	s_addc_u32 s43, s43, 0
	s_mov_b32 m0, s61
	v_lshl_add_u64 v[214:215], s[42:43], 0, v[130:131]
	ds_read_b128 v[178:181], v145 offset:32768
	ds_read_b128 v[182:185], v145 offset:33792
	ds_read_b128 v[186:189], v145 offset:34816
	ds_read_b128 v[190:193], v145 offset:35840
	ds_read_b128 v[202:205], v145 offset:36864
	ds_read_b128 v[206:209], v145 offset:37888
	ds_read_b128 v[220:223], v145 offset:38912
	ds_read_b128 v[224:227], v145 offset:39936
	global_load_lds_dwordx4 v[214:215], off
	v_lshl_add_u64 v[214:215], s[42:43], 0, v[132:133]
	s_mov_b32 m0, s62
	s_nop 0
	global_load_lds_dwordx4 v[214:215], off
	s_waitcnt vmcnt(8)
	s_waitcnt lgkmcnt(0)
	s_barrier
	v_mfma_f32_16x16x32_bf16 v[126:129], v[146:149], v[178:181], v[126:129]
	v_mfma_f32_16x16x32_bf16 v[122:125], v[154:157], v[178:181], v[122:125]
	v_mfma_f32_16x16x32_bf16 v[118:121], v[146:149], v[186:189], v[118:121]
	v_mfma_f32_16x16x32_bf16 v[110:113], v[154:157], v[186:189], v[110:113]
	v_mfma_f32_16x16x32_bf16 v[102:105], v[146:149], v[202:205], v[102:105]
	v_mfma_f32_16x16x32_bf16 v[94:97], v[154:157], v[202:205], v[94:97]
	v_mfma_f32_16x16x32_bf16 v[86:89], v[146:149], v[220:223], v[86:89]
	v_mfma_f32_16x16x32_bf16 v[78:81], v[154:157], v[220:223], v[78:81]
	v_mfma_f32_16x16x32_bf16 v[126:129], v[150:153], v[182:185], v[126:129]
	v_mfma_f32_16x16x32_bf16 v[122:125], v[158:161], v[182:185], v[122:125]
	v_mfma_f32_16x16x32_bf16 v[118:121], v[150:153], v[190:193], v[118:121]
	v_mfma_f32_16x16x32_bf16 v[110:113], v[158:161], v[190:193], v[110:113]
	v_mfma_f32_16x16x32_bf16 v[102:105], v[150:153], v[206:209], v[102:105]
	v_mfma_f32_16x16x32_bf16 v[94:97], v[158:161], v[206:209], v[94:97]
	v_mfma_f32_16x16x32_bf16 v[86:89], v[150:153], v[224:227], v[86:89]
	v_mfma_f32_16x16x32_bf16 v[78:81], v[158:161], v[224:227], v[78:81]
	v_mfma_f32_16x16x32_bf16 v[114:117], v[162:165], v[178:181], v[114:117]
	v_mfma_f32_16x16x32_bf16 v[106:109], v[170:173], v[178:181], v[106:109]
	v_mfma_f32_16x16x32_bf16 v[98:101], v[162:165], v[186:189], v[98:101]
	v_mfma_f32_16x16x32_bf16 v[90:93], v[170:173], v[186:189], v[90:93]
	v_mfma_f32_16x16x32_bf16 v[82:85], v[162:165], v[202:205], v[82:85]
	v_mfma_f32_16x16x32_bf16 v[74:77], v[170:173], v[202:205], v[74:77]
	v_mfma_f32_16x16x32_bf16 v[70:73], v[162:165], v[220:223], v[70:73]
	v_mfma_f32_16x16x32_bf16 v[66:69], v[170:173], v[220:223], v[66:69]
	v_mfma_f32_16x16x32_bf16 v[114:117], v[166:169], v[182:185], v[114:117]
	v_mfma_f32_16x16x32_bf16 v[106:109], v[174:177], v[182:185], v[106:109]
	v_mfma_f32_16x16x32_bf16 v[98:101], v[166:169], v[190:193], v[98:101]
	v_mfma_f32_16x16x32_bf16 v[90:93], v[174:177], v[190:193], v[90:93]
	v_mfma_f32_16x16x32_bf16 v[82:85], v[166:169], v[206:209], v[82:85]
	v_mfma_f32_16x16x32_bf16 v[74:77], v[174:177], v[206:209], v[74:77]
	v_mfma_f32_16x16x32_bf16 v[70:73], v[166:169], v[224:227], v[70:73]
	v_mfma_f32_16x16x32_bf16 v[66:69], v[174:177], v[224:227], v[66:69]
	s_barrier
	s_add_i32 s42, s45, s54
	v_lshl_add_u64 v[140:141], v[140:141], 0, s[84:85]
	s_mov_b32 m0, s42
	ds_read_b128 v[178:181], v145 offset:49152
	ds_read_b128 v[182:185], v145 offset:50176
	ds_read_b128 v[186:189], v145 offset:51200
	ds_read_b128 v[190:193], v145 offset:52224
	ds_read_b128 v[202:205], v145 offset:53248
	ds_read_b128 v[206:209], v145 offset:54272
	ds_read_b128 v[220:223], v145 offset:55296
	ds_read_b128 v[224:227], v145 offset:56320
	global_load_lds_dwordx4 v[140:141], off
	v_lshl_add_u64 v[140:141], v[194:195], 0, s[84:85]
	s_add_i32 m0, s42, 0x2000
	s_add_i32 s42, s73, s54
	global_load_lds_dwordx4 v[140:141], off
	v_lshl_add_u64 v[140:141], v[198:199], 0, s[84:85]
	s_mov_b32 m0, s42
	s_nop 0
	global_load_lds_dwordx4 v[140:141], off
	v_lshl_add_u64 v[140:141], v[200:201], 0, s[84:85]
	s_add_i32 m0, s42, 0x2000
	s_nop 0
	global_load_lds_dwordx4 v[140:141], off
	v_lshl_add_u64 v[140:141], v[210:211], 0, s[84:85]
	s_mov_b32 m0, s64
	s_nop 0
	global_load_lds_dwordx4 v[140:141], off
	v_lshl_add_u64 v[140:141], v[212:213], 0, s[84:85]
	s_mov_b32 m0, s65
	s_nop 0
	global_load_lds_dwordx4 v[140:141], off
	s_waitcnt vmcnt(8)
	s_waitcnt lgkmcnt(0)
	s_barrier
	v_mfma_f32_16x16x32_bf16 v[62:65], v[146:149], v[178:181], v[62:65]
	v_mfma_f32_16x16x32_bf16 v[58:61], v[154:157], v[178:181], v[58:61]
	v_mfma_f32_16x16x32_bf16 v[54:57], v[146:149], v[186:189], v[54:57]
	v_mfma_f32_16x16x32_bf16 v[46:49], v[154:157], v[186:189], v[46:49]
	v_mfma_f32_16x16x32_bf16 v[38:41], v[146:149], v[202:205], v[38:41]
	v_mfma_f32_16x16x32_bf16 v[30:33], v[154:157], v[202:205], v[30:33]
	v_mfma_f32_16x16x32_bf16 v[22:25], v[146:149], v[220:223], v[22:25]
	v_mfma_f32_16x16x32_bf16 v[14:17], v[154:157], v[220:223], v[14:17]
	v_mfma_f32_16x16x32_bf16 v[62:65], v[150:153], v[182:185], v[62:65]
	v_mfma_f32_16x16x32_bf16 v[58:61], v[158:161], v[182:185], v[58:61]
	v_mfma_f32_16x16x32_bf16 v[54:57], v[150:153], v[190:193], v[54:57]
	v_mfma_f32_16x16x32_bf16 v[46:49], v[158:161], v[190:193], v[46:49]
	v_mfma_f32_16x16x32_bf16 v[38:41], v[150:153], v[206:209], v[38:41]
	v_mfma_f32_16x16x32_bf16 v[30:33], v[158:161], v[206:209], v[30:33]
	v_mfma_f32_16x16x32_bf16 v[22:25], v[150:153], v[224:227], v[22:25]
	v_mfma_f32_16x16x32_bf16 v[14:17], v[158:161], v[224:227], v[14:17]
	v_mfma_f32_16x16x32_bf16 v[50:53], v[162:165], v[178:181], v[50:53]
	v_mfma_f32_16x16x32_bf16 v[42:45], v[170:173], v[178:181], v[42:45]
	v_mfma_f32_16x16x32_bf16 v[34:37], v[162:165], v[186:189], v[34:37]
	v_mfma_f32_16x16x32_bf16 v[26:29], v[170:173], v[186:189], v[26:29]
	v_mfma_f32_16x16x32_bf16 v[18:21], v[162:165], v[202:205], v[18:21]
	v_mfma_f32_16x16x32_bf16 v[10:13], v[170:173], v[202:205], v[10:13]
	v_mfma_f32_16x16x32_bf16 v[6:9], v[162:165], v[220:223], v[6:9]
	v_mfma_f32_16x16x32_bf16 v[2:5], v[170:173], v[220:223], v[2:5]
	v_mfma_f32_16x16x32_bf16 v[50:53], v[166:169], v[182:185], v[50:53]
	v_mfma_f32_16x16x32_bf16 v[42:45], v[174:177], v[182:185], v[42:45]
	v_mfma_f32_16x16x32_bf16 v[34:37], v[166:169], v[190:193], v[34:37]
	v_mfma_f32_16x16x32_bf16 v[26:29], v[174:177], v[190:193], v[26:29]
	v_mfma_f32_16x16x32_bf16 v[18:21], v[166:169], v[206:209], v[18:21]
	v_mfma_f32_16x16x32_bf16 v[10:13], v[174:177], v[206:209], v[10:13]
	v_mfma_f32_16x16x32_bf16 v[6:9], v[166:169], v[224:227], v[6:9]
	v_mfma_f32_16x16x32_bf16 v[2:5], v[174:177], v[224:227], v[2:5]
	s_barrier
	s_add_u32 vcc_lo, vcc_lo, 0x100
	s_addc_u32 vcc_hi, vcc_hi, 0
	s_add_u32 s82, s82, 0x100
	s_addc_u32 s83, s83, 0
	s_cmp_ge_u32 s72, s66
	s_mov_b32 s42, s72
	s_cbranch_scc1 .Lpeel_exit_bf
.LBB0_308:
	s_add_i32 s72, s42, 2
	s_add_u32 s73, vcc_lo, 0x80
	s_addc_u32 s43, vcc_hi, 0
	s_add_i32 s45, 0, 0x10000
	s_cmp_eq_u32 s63, s42
	s_cselect_b32 s43, s9, s43
	s_cselect_b32 s42, s8, s73
	v_add_u32_e32 v140, s45, v143
	s_cselect_b32 s75, s91, s83
	s_cselect_b32 s74, s90, s82
	s_add_i32 s73, 0, 0x14000
	ds_read_b128 v[146:149], v140
	ds_read_b128 v[150:153], v140 offset:1024
	ds_read_b128 v[154:157], v140 offset:2048
	ds_read_b128 v[158:161], v140 offset:3072
	v_add_u32_e32 v140, s73, v143
	ds_read_b128 v[162:165], v140
	ds_read_b128 v[166:169], v140 offset:1024
	ds_read_b128 v[170:173], v140 offset:2048
	ds_read_b128 v[174:177], v140 offset:3072
	v_lshl_add_u64 v[140:141], vcc, 0, v[136:137]
	s_add_i32 m0, s59, 0xc000
	ds_read_b128 v[178:181], v145
	ds_read_b128 v[182:185], v145 offset:1024
	ds_read_b128 v[186:189], v145 offset:2048
	ds_read_b128 v[190:193], v145 offset:3072
	ds_read_b128 v[202:205], v145 offset:4096
	ds_read_b128 v[206:209], v145 offset:5120
	ds_read_b128 v[220:223], v145 offset:6144
	ds_read_b128 v[224:227], v145 offset:7168
	global_load_lds_dwordx4 v[140:141], off
	v_lshl_add_u64 v[140:141], vcc, 0, v[138:139]
	s_add_i32 m0, s59, 0xe000
	s_nop 0
	global_load_lds_dwordx4 v[140:141], off
	s_waitcnt vmcnt(8)
	s_waitcnt lgkmcnt(0)
	s_barrier
	v_mfma_f32_16x16x32_bf16 v[126:129], v[146:149], v[178:181], v[126:129]
	v_mfma_f32_16x16x32_bf16 v[122:125], v[154:157], v[178:181], v[122:125]
	v_mfma_f32_16x16x32_bf16 v[118:121], v[146:149], v[186:189], v[118:121]
	v_mfma_f32_16x16x32_bf16 v[110:113], v[154:157], v[186:189], v[110:113]
	v_mfma_f32_16x16x32_bf16 v[102:105], v[146:149], v[202:205], v[102:105]
	v_mfma_f32_16x16x32_bf16 v[94:97], v[154:157], v[202:205], v[94:97]
	v_mfma_f32_16x16x32_bf16 v[86:89], v[146:149], v[220:223], v[86:89]
	v_mfma_f32_16x16x32_bf16 v[78:81], v[154:157], v[220:223], v[78:81]
	v_mfma_f32_16x16x32_bf16 v[126:129], v[150:153], v[182:185], v[126:129]
	v_mfma_f32_16x16x32_bf16 v[122:125], v[158:161], v[182:185], v[122:125]
	v_mfma_f32_16x16x32_bf16 v[118:121], v[150:153], v[190:193], v[118:121]
	v_mfma_f32_16x16x32_bf16 v[110:113], v[158:161], v[190:193], v[110:113]
	v_mfma_f32_16x16x32_bf16 v[102:105], v[150:153], v[206:209], v[102:105]
	v_mfma_f32_16x16x32_bf16 v[94:97], v[158:161], v[206:209], v[94:97]
	v_mfma_f32_16x16x32_bf16 v[86:89], v[150:153], v[224:227], v[86:89]
	v_mfma_f32_16x16x32_bf16 v[78:81], v[158:161], v[224:227], v[78:81]
	v_mfma_f32_16x16x32_bf16 v[114:117], v[162:165], v[178:181], v[114:117]
	v_mfma_f32_16x16x32_bf16 v[106:109], v[170:173], v[178:181], v[106:109]
	v_mfma_f32_16x16x32_bf16 v[98:101], v[162:165], v[186:189], v[98:101]
	v_mfma_f32_16x16x32_bf16 v[90:93], v[170:173], v[186:189], v[90:93]
	v_mfma_f32_16x16x32_bf16 v[82:85], v[162:165], v[202:205], v[82:85]
	v_mfma_f32_16x16x32_bf16 v[74:77], v[170:173], v[202:205], v[74:77]
	v_mfma_f32_16x16x32_bf16 v[70:73], v[162:165], v[220:223], v[70:73]
	v_mfma_f32_16x16x32_bf16 v[66:69], v[170:173], v[220:223], v[66:69]
	v_mfma_f32_16x16x32_bf16 v[114:117], v[166:169], v[182:185], v[114:117]
	v_mfma_f32_16x16x32_bf16 v[106:109], v[174:177], v[182:185], v[106:109]
	v_mfma_f32_16x16x32_bf16 v[98:101], v[166:169], v[190:193], v[98:101]
	v_mfma_f32_16x16x32_bf16 v[90:93], v[174:177], v[190:193], v[90:93]
	v_mfma_f32_16x16x32_bf16 v[82:85], v[166:169], v[206:209], v[82:85]
	v_mfma_f32_16x16x32_bf16 v[74:77], v[174:177], v[206:209], v[74:77]
	v_mfma_f32_16x16x32_bf16 v[70:73], v[166:169], v[224:227], v[70:73]
	v_mfma_f32_16x16x32_bf16 v[66:69], v[174:177], v[224:227], v[66:69]
	s_barrier
	s_add_i32 s45, s45, s54
	v_lshl_add_u64 v[140:141], s[74:75], 0, v[0:1]
	s_mov_b32 m0, s45
	ds_read_b128 v[178:181], v145 offset:16384
	ds_read_b128 v[182:185], v145 offset:17408
	ds_read_b128 v[186:189], v145 offset:18432
	ds_read_b128 v[190:193], v145 offset:19456
	ds_read_b128 v[202:205], v145 offset:20480
	ds_read_b128 v[206:209], v145 offset:21504
	ds_read_b128 v[220:223], v145 offset:22528
	ds_read_b128 v[224:227], v145 offset:23552
	global_load_lds_dwordx4 v[140:141], off
	s_add_i32 m0, s45, 0x2000
	v_lshl_add_u64 v[194:195], s[74:75], 0, v[134:135]
	s_add_u32 s74, s74, s80
	s_addc_u32 s75, s75, 0
	s_add_i32 s45, s73, s54
	global_load_lds_dwordx4 v[194:195], off
	v_lshl_add_u64 v[198:199], s[74:75], 0, v[0:1]
	s_mov_b32 m0, s45
	v_lshl_add_u64 v[200:201], s[74:75], 0, v[134:135]
	global_load_lds_dwordx4 v[198:199], off
	s_add_i32 m0, s45, 0x2000
	v_lshl_add_u64 v[210:211], s[42:43], 0, v[130:131]
	global_load_lds_dwordx4 v[200:201], off
	s_mov_b32 m0, s59
	v_lshl_add_u64 v[212:213], s[42:43], 0, v[132:133]
	global_load_lds_dwordx4 v[210:211], off
	s_mov_b32 m0, s60
	s_nop 0
	global_load_lds_dwordx4 v[212:213], off
	s_waitcnt vmcnt(8)
	s_waitcnt lgkmcnt(0)
	s_barrier
	v_mfma_f32_16x16x32_bf16 v[62:65], v[146:149], v[178:181], v[62:65]
	v_mfma_f32_16x16x32_bf16 v[58:61], v[154:157], v[178:181], v[58:61]
	v_mfma_f32_16x16x32_bf16 v[54:57], v[146:149], v[186:189], v[54:57]
	v_mfma_f32_16x16x32_bf16 v[46:49], v[154:157], v[186:189], v[46:49]
	v_mfma_f32_16x16x32_bf16 v[38:41], v[146:149], v[202:205], v[38:41]
	v_mfma_f32_16x16x32_bf16 v[30:33], v[154:157], v[202:205], v[30:33]
	v_mfma_f32_16x16x32_bf16 v[22:25], v[146:149], v[220:223], v[22:25]
	v_mfma_f32_16x16x32_bf16 v[14:17], v[154:157], v[220:223], v[14:17]
	v_mfma_f32_16x16x32_bf16 v[62:65], v[150:153], v[182:185], v[62:65]
	v_mfma_f32_16x16x32_bf16 v[58:61], v[158:161], v[182:185], v[58:61]
	v_mfma_f32_16x16x32_bf16 v[54:57], v[150:153], v[190:193], v[54:57]
	v_mfma_f32_16x16x32_bf16 v[46:49], v[158:161], v[190:193], v[46:49]
	v_mfma_f32_16x16x32_bf16 v[38:41], v[150:153], v[206:209], v[38:41]
	v_mfma_f32_16x16x32_bf16 v[30:33], v[158:161], v[206:209], v[30:33]
	v_mfma_f32_16x16x32_bf16 v[22:25], v[150:153], v[224:227], v[22:25]
	v_mfma_f32_16x16x32_bf16 v[14:17], v[158:161], v[224:227], v[14:17]
	v_mfma_f32_16x16x32_bf16 v[50:53], v[162:165], v[178:181], v[50:53]
	v_mfma_f32_16x16x32_bf16 v[42:45], v[170:173], v[178:181], v[42:45]
	v_mfma_f32_16x16x32_bf16 v[34:37], v[162:165], v[186:189], v[34:37]
	v_mfma_f32_16x16x32_bf16 v[26:29], v[170:173], v[186:189], v[26:29]
	v_mfma_f32_16x16x32_bf16 v[18:21], v[162:165], v[202:205], v[18:21]
	v_mfma_f32_16x16x32_bf16 v[10:13], v[170:173], v[202:205], v[10:13]
	v_mfma_f32_16x16x32_bf16 v[6:9], v[162:165], v[220:223], v[6:9]
	v_mfma_f32_16x16x32_bf16 v[2:5], v[170:173], v[220:223], v[2:5]
	v_mfma_f32_16x16x32_bf16 v[50:53], v[166:169], v[182:185], v[50:53]
	v_mfma_f32_16x16x32_bf16 v[42:45], v[174:177], v[182:185], v[42:45]
	v_mfma_f32_16x16x32_bf16 v[34:37], v[166:169], v[190:193], v[34:37]
	v_mfma_f32_16x16x32_bf16 v[26:29], v[174:177], v[190:193], v[26:29]
	v_mfma_f32_16x16x32_bf16 v[18:21], v[166:169], v[206:209], v[18:21]
	v_mfma_f32_16x16x32_bf16 v[10:13], v[174:177], v[206:209], v[10:13]
	v_mfma_f32_16x16x32_bf16 v[6:9], v[166:169], v[224:227], v[6:9]
	v_mfma_f32_16x16x32_bf16 v[2:5], v[174:177], v[224:227], v[2:5]
	s_barrier
	s_add_i32 s45, 0, 0x18000
	s_add_i32 s73, 0, 0x1c000
	v_add_u32_e32 v158, s45, v143
	v_add_u32_e32 v174, s73, v143
	ds_read_b128 v[146:149], v158
	ds_read_b128 v[150:153], v158 offset:1024
	ds_read_b128 v[154:157], v158 offset:2048
	ds_read_b128 v[158:161], v158 offset:3072
	ds_read_b128 v[162:165], v174
	ds_read_b128 v[166:169], v174 offset:1024
	ds_read_b128 v[170:173], v174 offset:2048
	ds_read_b128 v[174:177], v174 offset:3072
	s_add_u32 s42, s42, s80
	s_addc_u32 s43, s43, 0
	s_mov_b32 m0, s61
	v_lshl_add_u64 v[214:215], s[42:43], 0, v[130:131]
	ds_read_b128 v[178:181], v145 offset:32768
	ds_read_b128 v[182:185], v145 offset:33792
	ds_read_b128 v[186:189], v145 offset:34816
	ds_read_b128 v[190:193], v145 offset:35840
	ds_read_b128 v[202:205], v145 offset:36864
	ds_read_b128 v[206:209], v145 offset:37888
	ds_read_b128 v[220:223], v145 offset:38912
	ds_read_b128 v[224:227], v145 offset:39936
	global_load_lds_dwordx4 v[214:215], off
	v_lshl_add_u64 v[214:215], s[42:43], 0, v[132:133]
	s_mov_b32 m0, s62
	s_nop 0
	global_load_lds_dwordx4 v[214:215], off
	s_waitcnt vmcnt(8)
	s_waitcnt lgkmcnt(0)
	s_barrier
	v_mfma_f32_16x16x32_bf16 v[126:129], v[146:149], v[178:181], v[126:129]
	v_mfma_f32_16x16x32_bf16 v[122:125], v[154:157], v[178:181], v[122:125]
	v_mfma_f32_16x16x32_bf16 v[118:121], v[146:149], v[186:189], v[118:121]
	v_mfma_f32_16x16x32_bf16 v[110:113], v[154:157], v[186:189], v[110:113]
	v_mfma_f32_16x16x32_bf16 v[102:105], v[146:149], v[202:205], v[102:105]
	v_mfma_f32_16x16x32_bf16 v[94:97], v[154:157], v[202:205], v[94:97]
	v_mfma_f32_16x16x32_bf16 v[86:89], v[146:149], v[220:223], v[86:89]
	v_mfma_f32_16x16x32_bf16 v[78:81], v[154:157], v[220:223], v[78:81]
	v_mfma_f32_16x16x32_bf16 v[126:129], v[150:153], v[182:185], v[126:129]
	v_mfma_f32_16x16x32_bf16 v[122:125], v[158:161], v[182:185], v[122:125]
	v_mfma_f32_16x16x32_bf16 v[118:121], v[150:153], v[190:193], v[118:121]
	v_mfma_f32_16x16x32_bf16 v[110:113], v[158:161], v[190:193], v[110:113]
	v_mfma_f32_16x16x32_bf16 v[102:105], v[150:153], v[206:209], v[102:105]
	v_mfma_f32_16x16x32_bf16 v[94:97], v[158:161], v[206:209], v[94:97]
	v_mfma_f32_16x16x32_bf16 v[86:89], v[150:153], v[224:227], v[86:89]
	v_mfma_f32_16x16x32_bf16 v[78:81], v[158:161], v[224:227], v[78:81]
	v_mfma_f32_16x16x32_bf16 v[114:117], v[162:165], v[178:181], v[114:117]
	v_mfma_f32_16x16x32_bf16 v[106:109], v[170:173], v[178:181], v[106:109]
	v_mfma_f32_16x16x32_bf16 v[98:101], v[162:165], v[186:189], v[98:101]
	v_mfma_f32_16x16x32_bf16 v[90:93], v[170:173], v[186:189], v[90:93]
	v_mfma_f32_16x16x32_bf16 v[82:85], v[162:165], v[202:205], v[82:85]
	v_mfma_f32_16x16x32_bf16 v[74:77], v[170:173], v[202:205], v[74:77]
	v_mfma_f32_16x16x32_bf16 v[70:73], v[162:165], v[220:223], v[70:73]
	v_mfma_f32_16x16x32_bf16 v[66:69], v[170:173], v[220:223], v[66:69]
	v_mfma_f32_16x16x32_bf16 v[114:117], v[166:169], v[182:185], v[114:117]
	v_mfma_f32_16x16x32_bf16 v[106:109], v[174:177], v[182:185], v[106:109]
	v_mfma_f32_16x16x32_bf16 v[98:101], v[166:169], v[190:193], v[98:101]
	v_mfma_f32_16x16x32_bf16 v[90:93], v[174:177], v[190:193], v[90:93]
	v_mfma_f32_16x16x32_bf16 v[82:85], v[166:169], v[206:209], v[82:85]
	v_mfma_f32_16x16x32_bf16 v[74:77], v[174:177], v[206:209], v[74:77]
	v_mfma_f32_16x16x32_bf16 v[70:73], v[166:169], v[224:227], v[70:73]
	v_mfma_f32_16x16x32_bf16 v[66:69], v[174:177], v[224:227], v[66:69]
	s_barrier
	s_add_i32 s42, s45, s54
	v_lshl_add_u64 v[140:141], v[140:141], 0, s[84:85]
	s_mov_b32 m0, s42
	ds_read_b128 v[178:181], v145 offset:49152
	ds_read_b128 v[182:185], v145 offset:50176
	ds_read_b128 v[186:189], v145 offset:51200
	ds_read_b128 v[190:193], v145 offset:52224
	ds_read_b128 v[202:205], v145 offset:53248
	ds_read_b128 v[206:209], v145 offset:54272
	ds_read_b128 v[220:223], v145 offset:55296
	ds_read_b128 v[224:227], v145 offset:56320
	global_load_lds_dwordx4 v[140:141], off
	v_lshl_add_u64 v[140:141], v[194:195], 0, s[84:85]
	s_add_i32 m0, s42, 0x2000
	s_add_i32 s42, s73, s54
	global_load_lds_dwordx4 v[140:141], off
	v_lshl_add_u64 v[140:141], v[198:199], 0, s[84:85]
	s_mov_b32 m0, s42
	s_nop 0
	global_load_lds_dwordx4 v[140:141], off
	v_lshl_add_u64 v[140:141], v[200:201], 0, s[84:85]
	s_add_i32 m0, s42, 0x2000
	s_nop 0
	global_load_lds_dwordx4 v[140:141], off
	v_lshl_add_u64 v[140:141], v[210:211], 0, s[84:85]
	s_mov_b32 m0, s64
	s_nop 0
	global_load_lds_dwordx4 v[140:141], off
	v_lshl_add_u64 v[140:141], v[212:213], 0, s[84:85]
	s_mov_b32 m0, s65
	s_nop 0
	global_load_lds_dwordx4 v[140:141], off
	s_waitcnt vmcnt(8)
	s_waitcnt lgkmcnt(0)
	s_barrier
	v_mfma_f32_16x16x32_bf16 v[62:65], v[146:149], v[178:181], v[62:65]
	v_mfma_f32_16x16x32_bf16 v[58:61], v[154:157], v[178:181], v[58:61]
	v_mfma_f32_16x16x32_bf16 v[54:57], v[146:149], v[186:189], v[54:57]
	v_mfma_f32_16x16x32_bf16 v[46:49], v[154:157], v[186:189], v[46:49]
	v_mfma_f32_16x16x32_bf16 v[38:41], v[146:149], v[202:205], v[38:41]
	v_mfma_f32_16x16x32_bf16 v[30:33], v[154:157], v[202:205], v[30:33]
	v_mfma_f32_16x16x32_bf16 v[22:25], v[146:149], v[220:223], v[22:25]
	v_mfma_f32_16x16x32_bf16 v[14:17], v[154:157], v[220:223], v[14:17]
	v_mfma_f32_16x16x32_bf16 v[62:65], v[150:153], v[182:185], v[62:65]
	v_mfma_f32_16x16x32_bf16 v[58:61], v[158:161], v[182:185], v[58:61]
	v_mfma_f32_16x16x32_bf16 v[54:57], v[150:153], v[190:193], v[54:57]
	v_mfma_f32_16x16x32_bf16 v[46:49], v[158:161], v[190:193], v[46:49]
	v_mfma_f32_16x16x32_bf16 v[38:41], v[150:153], v[206:209], v[38:41]
	v_mfma_f32_16x16x32_bf16 v[30:33], v[158:161], v[206:209], v[30:33]
	v_mfma_f32_16x16x32_bf16 v[22:25], v[150:153], v[224:227], v[22:25]
	v_mfma_f32_16x16x32_bf16 v[14:17], v[158:161], v[224:227], v[14:17]
	v_mfma_f32_16x16x32_bf16 v[50:53], v[162:165], v[178:181], v[50:53]
	v_mfma_f32_16x16x32_bf16 v[42:45], v[170:173], v[178:181], v[42:45]
	v_mfma_f32_16x16x32_bf16 v[34:37], v[162:165], v[186:189], v[34:37]
	v_mfma_f32_16x16x32_bf16 v[26:29], v[170:173], v[186:189], v[26:29]
	v_mfma_f32_16x16x32_bf16 v[18:21], v[162:165], v[202:205], v[18:21]
	v_mfma_f32_16x16x32_bf16 v[10:13], v[170:173], v[202:205], v[10:13]
	v_mfma_f32_16x16x32_bf16 v[6:9], v[162:165], v[220:223], v[6:9]
	v_mfma_f32_16x16x32_bf16 v[2:5], v[170:173], v[220:223], v[2:5]
	v_mfma_f32_16x16x32_bf16 v[50:53], v[166:169], v[182:185], v[50:53]
	v_mfma_f32_16x16x32_bf16 v[42:45], v[174:177], v[182:185], v[42:45]
	v_mfma_f32_16x16x32_bf16 v[34:37], v[166:169], v[190:193], v[34:37]
	v_mfma_f32_16x16x32_bf16 v[26:29], v[174:177], v[190:193], v[26:29]
	v_mfma_f32_16x16x32_bf16 v[18:21], v[166:169], v[206:209], v[18:21]
	v_mfma_f32_16x16x32_bf16 v[10:13], v[174:177], v[206:209], v[10:13]
	v_mfma_f32_16x16x32_bf16 v[6:9], v[166:169], v[224:227], v[6:9]
	v_mfma_f32_16x16x32_bf16 v[2:5], v[174:177], v[224:227], v[2:5]
	s_barrier
	s_add_u32 vcc_lo, vcc_lo, 0x100
	s_addc_u32 vcc_hi, vcc_hi, 0
	s_add_u32 s82, s82, 0x100
	s_addc_u32 s83, s83, 0
	s_cmp_ge_u32 s72, s66
	s_mov_b32 s42, s72
	s_cbranch_scc0 .LBB0_308

.LBB0_351:
	s_add_u32 s8, s76, 0x80
	s_addc_u32 s9, s77, 0
	s_add_u32 s59, s36, 0x100
	s_addc_u32 s60, s37, 0
	s_mov_b32 s36, 0
	s_add_i32 s61, s36, 2
	s_add_u32 s45, s8, 0x80
	s_addc_u32 s37, s9, 0
	s_add_i32 s64, 0, 0x10000
	s_cmp_eq_u32 s48, s36
	s_cselect_b32 s37, s39, s37
	s_cselect_b32 s36, s38, s45
	s_cselect_b32 s63, s41, s60
	s_cselect_b32 s62, s40, s59
	s_add_i32 s45, 0, 0x14000
	v_add_u32_e32 v158, s64, v148
	v_add_u32_e32 v174, s45, v148
	ds_read_b128 v[144:147], v158
	ds_read_b128 v[150:153], v158 offset:1024
	ds_read_b128 v[154:157], v158 offset:2048
	ds_read_b128 v[158:161], v158 offset:3072
	ds_read_b128 v[162:165], v174
	ds_read_b128 v[166:169], v174 offset:1024
	ds_read_b128 v[170:173], v174 offset:2048
	ds_read_b128 v[174:177], v174 offset:3072
	v_lshl_add_u64 v[194:195], s[8:9], 0, v[140:141]
	s_add_i32 m0, s82, 0xc000
	ds_read_b128 v[178:181], v149
	ds_read_b128 v[182:185], v149 offset:1024
	ds_read_b128 v[186:189], v149 offset:2048
	ds_read_b128 v[190:193], v149 offset:3072
	ds_read_b128 v[202:205], v149 offset:4096
	ds_read_b128 v[206:209], v149 offset:5120
	ds_read_b128 v[220:223], v149 offset:6144
	ds_read_b128 v[224:227], v149 offset:7168
	global_load_lds_dwordx4 v[194:195], off
	v_lshl_add_u64 v[194:195], s[8:9], 0, v[142:143]
	s_add_i32 m0, s82, 0xe000
	s_nop 0
	global_load_lds_dwordx4 v[194:195], off
	s_waitcnt vmcnt(8)
	s_waitcnt lgkmcnt(0)
	s_barrier
	v_mfma_f32_16x16x32_bf16 v[126:129], v[144:147], v[178:181], 0
	v_mfma_f32_16x16x32_bf16 v[122:125], v[154:157], v[178:181], 0
	v_mfma_f32_16x16x32_bf16 v[110:113], v[144:147], v[186:189], 0
	v_mfma_f32_16x16x32_bf16 v[106:109], v[154:157], v[186:189], 0
	v_mfma_f32_16x16x32_bf16 v[94:97], v[144:147], v[202:205], 0
	v_mfma_f32_16x16x32_bf16 v[90:93], v[154:157], v[202:205], 0
	v_mfma_f32_16x16x32_bf16 v[78:81], v[144:147], v[220:223], 0
	v_mfma_f32_16x16x32_bf16 v[74:77], v[154:157], v[220:223], 0
	v_mfma_f32_16x16x32_bf16 v[126:129], v[150:153], v[182:185], v[126:129]
	v_mfma_f32_16x16x32_bf16 v[122:125], v[158:161], v[182:185], v[122:125]
	v_mfma_f32_16x16x32_bf16 v[110:113], v[150:153], v[190:193], v[110:113]
	v_mfma_f32_16x16x32_bf16 v[106:109], v[158:161], v[190:193], v[106:109]
	v_mfma_f32_16x16x32_bf16 v[94:97], v[150:153], v[206:209], v[94:97]
	v_mfma_f32_16x16x32_bf16 v[90:93], v[158:161], v[206:209], v[90:93]
	v_mfma_f32_16x16x32_bf16 v[78:81], v[150:153], v[224:227], v[78:81]
	v_mfma_f32_16x16x32_bf16 v[74:77], v[158:161], v[224:227], v[74:77]
	v_mfma_f32_16x16x32_bf16 v[118:121], v[162:165], v[178:181], 0
	v_mfma_f32_16x16x32_bf16 v[114:117], v[170:173], v[178:181], 0
	v_mfma_f32_16x16x32_bf16 v[102:105], v[162:165], v[186:189], 0
	v_mfma_f32_16x16x32_bf16 v[98:101], v[170:173], v[186:189], 0
	v_mfma_f32_16x16x32_bf16 v[86:89], v[162:165], v[202:205], 0
	v_mfma_f32_16x16x32_bf16 v[82:85], v[170:173], v[202:205], 0
	v_mfma_f32_16x16x32_bf16 v[70:73], v[162:165], v[220:223], 0
	v_mfma_f32_16x16x32_bf16 v[66:69], v[170:173], v[220:223], 0
	v_mfma_f32_16x16x32_bf16 v[118:121], v[166:169], v[182:185], v[118:121]
	v_mfma_f32_16x16x32_bf16 v[114:117], v[174:177], v[182:185], v[114:117]
	v_mfma_f32_16x16x32_bf16 v[102:105], v[166:169], v[190:193], v[102:105]
	v_mfma_f32_16x16x32_bf16 v[98:101], v[174:177], v[190:193], v[98:101]
	v_mfma_f32_16x16x32_bf16 v[86:89], v[166:169], v[206:209], v[86:89]
	v_mfma_f32_16x16x32_bf16 v[82:85], v[174:177], v[206:209], v[82:85]
	v_mfma_f32_16x16x32_bf16 v[70:73], v[166:169], v[224:227], v[70:73]
	v_mfma_f32_16x16x32_bf16 v[66:69], v[174:177], v[224:227], v[66:69]
	s_barrier
	s_add_i32 s64, s64, s79
	v_lshl_add_u64 v[194:195], s[62:63], 0, v[132:133]
	s_mov_b32 m0, s64
	ds_read_b128 v[178:181], v149 offset:16384
	ds_read_b128 v[182:185], v149 offset:17408
	ds_read_b128 v[186:189], v149 offset:18432
	ds_read_b128 v[190:193], v149 offset:19456
	ds_read_b128 v[202:205], v149 offset:20480
	ds_read_b128 v[206:209], v149 offset:21504
	ds_read_b128 v[220:223], v149 offset:22528
	ds_read_b128 v[224:227], v149 offset:23552
	global_load_lds_dwordx4 v[194:195], off
	s_add_i32 m0, s64, 0x2000
	v_lshl_add_u64 v[198:199], s[62:63], 0, v[136:137]
	s_add_u32 s62, s62, s80
	s_addc_u32 s63, s63, 0
	s_add_i32 s45, s45, s79
	global_load_lds_dwordx4 v[198:199], off
	v_lshl_add_u64 v[200:201], s[62:63], 0, v[132:133]
	s_mov_b32 m0, s45
	v_lshl_add_u64 v[210:211], s[62:63], 0, v[136:137]
	global_load_lds_dwordx4 v[200:201], off
	s_add_i32 m0, s45, 0x2000
	v_lshl_add_u64 v[212:213], s[36:37], 0, v[130:131]
	global_load_lds_dwordx4 v[210:211], off
	s_mov_b32 m0, s82
	v_lshl_add_u64 v[214:215], s[36:37], 0, v[134:135]
	global_load_lds_dwordx4 v[212:213], off
	s_mov_b32 m0, s83
	s_nop 0
	global_load_lds_dwordx4 v[214:215], off
	s_waitcnt vmcnt(8)
	s_waitcnt lgkmcnt(0)
	s_barrier
	v_mfma_f32_16x16x32_bf16 v[62:65], v[144:147], v[178:181], 0
	v_mfma_f32_16x16x32_bf16 v[58:61], v[154:157], v[178:181], 0
	v_mfma_f32_16x16x32_bf16 v[46:49], v[144:147], v[186:189], 0
	v_mfma_f32_16x16x32_bf16 v[42:45], v[154:157], v[186:189], 0
	v_mfma_f32_16x16x32_bf16 v[30:33], v[144:147], v[202:205], 0
	v_mfma_f32_16x16x32_bf16 v[26:29], v[154:157], v[202:205], 0
	v_mfma_f32_16x16x32_bf16 v[14:17], v[144:147], v[220:223], 0
	v_mfma_f32_16x16x32_bf16 v[10:13], v[154:157], v[220:223], 0
	v_mfma_f32_16x16x32_bf16 v[62:65], v[150:153], v[182:185], v[62:65]
	v_mfma_f32_16x16x32_bf16 v[58:61], v[158:161], v[182:185], v[58:61]
	v_mfma_f32_16x16x32_bf16 v[46:49], v[150:153], v[190:193], v[46:49]
	v_mfma_f32_16x16x32_bf16 v[42:45], v[158:161], v[190:193], v[42:45]
	v_mfma_f32_16x16x32_bf16 v[30:33], v[150:153], v[206:209], v[30:33]
	v_mfma_f32_16x16x32_bf16 v[26:29], v[158:161], v[206:209], v[26:29]
	v_mfma_f32_16x16x32_bf16 v[14:17], v[150:153], v[224:227], v[14:17]
	v_mfma_f32_16x16x32_bf16 v[10:13], v[158:161], v[224:227], v[10:13]
	v_mfma_f32_16x16x32_bf16 v[54:57], v[162:165], v[178:181], 0
	v_mfma_f32_16x16x32_bf16 v[50:53], v[170:173], v[178:181], 0
	v_mfma_f32_16x16x32_bf16 v[38:41], v[162:165], v[186:189], 0
	v_mfma_f32_16x16x32_bf16 v[34:37], v[170:173], v[186:189], 0
	v_mfma_f32_16x16x32_bf16 v[22:25], v[162:165], v[202:205], 0
	v_mfma_f32_16x16x32_bf16 v[18:21], v[170:173], v[202:205], 0
	v_mfma_f32_16x16x32_bf16 v[6:9], v[162:165], v[220:223], 0
	v_mfma_f32_16x16x32_bf16 v[2:5], v[170:173], v[220:223], 0
	v_mfma_f32_16x16x32_bf16 v[54:57], v[166:169], v[182:185], v[54:57]
	v_mfma_f32_16x16x32_bf16 v[50:53], v[174:177], v[182:185], v[50:53]
	v_mfma_f32_16x16x32_bf16 v[38:41], v[166:169], v[190:193], v[38:41]
	v_mfma_f32_16x16x32_bf16 v[34:37], v[174:177], v[190:193], v[34:37]
	v_mfma_f32_16x16x32_bf16 v[22:25], v[166:169], v[206:209], v[22:25]
	v_mfma_f32_16x16x32_bf16 v[18:21], v[174:177], v[206:209], v[18:21]
	v_mfma_f32_16x16x32_bf16 v[6:9], v[166:169], v[224:227], v[6:9]
	v_mfma_f32_16x16x32_bf16 v[2:5], v[174:177], v[224:227], v[2:5]
	s_barrier
	s_add_i32 s45, 0, 0x18000
	s_add_i32 s62, 0, 0x1c000
	v_add_u32_e32 v158, s45, v148
	v_add_u32_e32 v174, s62, v148
	ds_read_b128 v[144:147], v158
	ds_read_b128 v[150:153], v158 offset:1024
	ds_read_b128 v[154:157], v158 offset:2048
	ds_read_b128 v[158:161], v158 offset:3072
	ds_read_b128 v[162:165], v174
	ds_read_b128 v[166:169], v174 offset:1024
	ds_read_b128 v[170:173], v174 offset:2048
	ds_read_b128 v[174:177], v174 offset:3072
	s_add_u32 s36, s36, s80
	s_addc_u32 s37, s37, 0
	s_mov_b32 m0, s86
	v_lshl_add_u64 v[216:217], s[36:37], 0, v[130:131]
	ds_read_b128 v[178:181], v149 offset:32768
	ds_read_b128 v[182:185], v149 offset:33792
	ds_read_b128 v[186:189], v149 offset:34816
	ds_read_b128 v[190:193], v149 offset:35840
	ds_read_b128 v[202:205], v149 offset:36864
	ds_read_b128 v[206:209], v149 offset:37888
	ds_read_b128 v[220:223], v149 offset:38912
	ds_read_b128 v[224:227], v149 offset:39936
	global_load_lds_dwordx4 v[216:217], off
	v_lshl_add_u64 v[216:217], s[36:37], 0, v[134:135]
	s_mov_b32 m0, s87
	s_nop 0
	global_load_lds_dwordx4 v[216:217], off
	s_waitcnt vmcnt(8)
	s_waitcnt lgkmcnt(0)
	s_barrier
	v_mfma_f32_16x16x32_bf16 v[126:129], v[144:147], v[178:181], v[126:129]
	v_mfma_f32_16x16x32_bf16 v[122:125], v[154:157], v[178:181], v[122:125]
	v_mfma_f32_16x16x32_bf16 v[110:113], v[144:147], v[186:189], v[110:113]
	v_mfma_f32_16x16x32_bf16 v[106:109], v[154:157], v[186:189], v[106:109]
	v_mfma_f32_16x16x32_bf16 v[94:97], v[144:147], v[202:205], v[94:97]
	v_mfma_f32_16x16x32_bf16 v[90:93], v[154:157], v[202:205], v[90:93]
	v_mfma_f32_16x16x32_bf16 v[78:81], v[144:147], v[220:223], v[78:81]
	v_mfma_f32_16x16x32_bf16 v[74:77], v[154:157], v[220:223], v[74:77]
	v_mfma_f32_16x16x32_bf16 v[126:129], v[150:153], v[182:185], v[126:129]
	v_mfma_f32_16x16x32_bf16 v[122:125], v[158:161], v[182:185], v[122:125]
	v_mfma_f32_16x16x32_bf16 v[110:113], v[150:153], v[190:193], v[110:113]
	v_mfma_f32_16x16x32_bf16 v[106:109], v[158:161], v[190:193], v[106:109]
	v_mfma_f32_16x16x32_bf16 v[94:97], v[150:153], v[206:209], v[94:97]
	v_mfma_f32_16x16x32_bf16 v[90:93], v[158:161], v[206:209], v[90:93]
	v_mfma_f32_16x16x32_bf16 v[78:81], v[150:153], v[224:227], v[78:81]
	v_mfma_f32_16x16x32_bf16 v[74:77], v[158:161], v[224:227], v[74:77]
	v_mfma_f32_16x16x32_bf16 v[118:121], v[162:165], v[178:181], v[118:121]
	v_mfma_f32_16x16x32_bf16 v[114:117], v[170:173], v[178:181], v[114:117]
	v_mfma_f32_16x16x32_bf16 v[102:105], v[162:165], v[186:189], v[102:105]
	v_mfma_f32_16x16x32_bf16 v[98:101], v[170:173], v[186:189], v[98:101]
	v_mfma_f32_16x16x32_bf16 v[86:89], v[162:165], v[202:205], v[86:89]
	v_mfma_f32_16x16x32_bf16 v[82:85], v[170:173], v[202:205], v[82:85]
	v_mfma_f32_16x16x32_bf16 v[70:73], v[162:165], v[220:223], v[70:73]
	v_mfma_f32_16x16x32_bf16 v[66:69], v[170:173], v[220:223], v[66:69]
	v_mfma_f32_16x16x32_bf16 v[118:121], v[166:169], v[182:185], v[118:121]
	v_mfma_f32_16x16x32_bf16 v[114:117], v[174:177], v[182:185], v[114:117]
	v_mfma_f32_16x16x32_bf16 v[102:105], v[166:169], v[190:193], v[102:105]
	v_mfma_f32_16x16x32_bf16 v[98:101], v[174:177], v[190:193], v[98:101]
	v_mfma_f32_16x16x32_bf16 v[86:89], v[166:169], v[206:209], v[86:89]
	v_mfma_f32_16x16x32_bf16 v[82:85], v[174:177], v[206:209], v[82:85]
	v_mfma_f32_16x16x32_bf16 v[70:73], v[166:169], v[224:227], v[70:73]
	v_mfma_f32_16x16x32_bf16 v[66:69], v[174:177], v[224:227], v[66:69]
	s_barrier
	s_add_i32 s36, s45, s79
	v_lshl_add_u64 v[194:195], v[194:195], 0, s[84:85]
	s_mov_b32 m0, s36
	ds_read_b128 v[178:181], v149 offset:49152
	ds_read_b128 v[182:185], v149 offset:50176
	ds_read_b128 v[186:189], v149 offset:51200
	ds_read_b128 v[190:193], v149 offset:52224
	ds_read_b128 v[202:205], v149 offset:53248
	ds_read_b128 v[206:209], v149 offset:54272
	ds_read_b128 v[220:223], v149 offset:55296
	ds_read_b128 v[224:227], v149 offset:56320
	global_load_lds_dwordx4 v[194:195], off
	v_lshl_add_u64 v[194:195], v[198:199], 0, s[84:85]
	s_add_i32 m0, s36, 0x2000
	s_add_i32 s36, s62, s79
	global_load_lds_dwordx4 v[194:195], off
	v_lshl_add_u64 v[194:195], v[200:201], 0, s[84:85]
	s_mov_b32 m0, s36
	s_nop 0
	global_load_lds_dwordx4 v[194:195], off
	v_lshl_add_u64 v[194:195], v[210:211], 0, s[84:85]
	s_add_i32 m0, s36, 0x2000
	s_nop 0
	global_load_lds_dwordx4 v[194:195], off
	v_lshl_add_u64 v[194:195], v[212:213], 0, s[84:85]
	s_mov_b32 m0, s46
	s_nop 0
	global_load_lds_dwordx4 v[194:195], off
	v_lshl_add_u64 v[194:195], v[214:215], 0, s[84:85]
	s_mov_b32 m0, s47
	s_nop 0
	global_load_lds_dwordx4 v[194:195], off
	s_waitcnt vmcnt(8)
	s_waitcnt lgkmcnt(0)
	s_barrier
	v_mfma_f32_16x16x32_bf16 v[62:65], v[144:147], v[178:181], v[62:65]
	v_mfma_f32_16x16x32_bf16 v[58:61], v[154:157], v[178:181], v[58:61]
	v_mfma_f32_16x16x32_bf16 v[46:49], v[144:147], v[186:189], v[46:49]
	v_mfma_f32_16x16x32_bf16 v[42:45], v[154:157], v[186:189], v[42:45]
	v_mfma_f32_16x16x32_bf16 v[30:33], v[144:147], v[202:205], v[30:33]
	v_mfma_f32_16x16x32_bf16 v[26:29], v[154:157], v[202:205], v[26:29]
	v_mfma_f32_16x16x32_bf16 v[14:17], v[144:147], v[220:223], v[14:17]
	v_mfma_f32_16x16x32_bf16 v[10:13], v[154:157], v[220:223], v[10:13]
	v_mfma_f32_16x16x32_bf16 v[62:65], v[150:153], v[182:185], v[62:65]
	v_mfma_f32_16x16x32_bf16 v[58:61], v[158:161], v[182:185], v[58:61]
	v_mfma_f32_16x16x32_bf16 v[46:49], v[150:153], v[190:193], v[46:49]
	v_mfma_f32_16x16x32_bf16 v[42:45], v[158:161], v[190:193], v[42:45]
	v_mfma_f32_16x16x32_bf16 v[30:33], v[150:153], v[206:209], v[30:33]
	v_mfma_f32_16x16x32_bf16 v[26:29], v[158:161], v[206:209], v[26:29]
	v_mfma_f32_16x16x32_bf16 v[14:17], v[150:153], v[224:227], v[14:17]
	v_mfma_f32_16x16x32_bf16 v[10:13], v[158:161], v[224:227], v[10:13]
	v_mfma_f32_16x16x32_bf16 v[54:57], v[162:165], v[178:181], v[54:57]
	v_mfma_f32_16x16x32_bf16 v[50:53], v[170:173], v[178:181], v[50:53]
	v_mfma_f32_16x16x32_bf16 v[38:41], v[162:165], v[186:189], v[38:41]
	v_mfma_f32_16x16x32_bf16 v[34:37], v[170:173], v[186:189], v[34:37]
	v_mfma_f32_16x16x32_bf16 v[22:25], v[162:165], v[202:205], v[22:25]
	v_mfma_f32_16x16x32_bf16 v[18:21], v[170:173], v[202:205], v[18:21]
	v_mfma_f32_16x16x32_bf16 v[6:9], v[162:165], v[220:223], v[6:9]
	v_mfma_f32_16x16x32_bf16 v[2:5], v[170:173], v[220:223], v[2:5]
	v_mfma_f32_16x16x32_bf16 v[54:57], v[166:169], v[182:185], v[54:57]
	v_mfma_f32_16x16x32_bf16 v[50:53], v[174:177], v[182:185], v[50:53]
	v_mfma_f32_16x16x32_bf16 v[38:41], v[166:169], v[190:193], v[38:41]
	v_mfma_f32_16x16x32_bf16 v[34:37], v[174:177], v[190:193], v[34:37]
	v_mfma_f32_16x16x32_bf16 v[22:25], v[166:169], v[206:209], v[22:25]
	v_mfma_f32_16x16x32_bf16 v[18:21], v[174:177], v[206:209], v[18:21]
	v_mfma_f32_16x16x32_bf16 v[6:9], v[166:169], v[224:227], v[6:9]
	v_mfma_f32_16x16x32_bf16 v[2:5], v[174:177], v[224:227], v[2:5]
	s_barrier
	s_add_u32 s8, s8, 0x100
	s_addc_u32 s9, s9, 0
	s_add_u32 s59, s59, 0x100
	s_addc_u32 s60, s60, 0
	s_cmp_ge_u32 s61, s90
	s_mov_b32 s36, s61
	s_cbranch_scc1 .Lpeel_exit_vt
.LBB0_352:
	s_add_i32 s61, s36, 2
	s_add_u32 s45, s8, 0x80
	s_addc_u32 s37, s9, 0
	s_add_i32 s64, 0, 0x10000
	s_cmp_eq_u32 s48, s36
	s_cselect_b32 s37, s39, s37
	s_cselect_b32 s36, s38, s45
	s_cselect_b32 s63, s41, s60
	s_cselect_b32 s62, s40, s59
	s_add_i32 s45, 0, 0x14000
	v_add_u32_e32 v158, s64, v148
	v_add_u32_e32 v174, s45, v148
	ds_read_b128 v[144:147], v158
	ds_read_b128 v[150:153], v158 offset:1024
	ds_read_b128 v[154:157], v158 offset:2048
	ds_read_b128 v[158:161], v158 offset:3072
	ds_read_b128 v[162:165], v174
	ds_read_b128 v[166:169], v174 offset:1024
	ds_read_b128 v[170:173], v174 offset:2048
	ds_read_b128 v[174:177], v174 offset:3072
	v_lshl_add_u64 v[194:195], s[8:9], 0, v[140:141]
	s_add_i32 m0, s82, 0xc000
	ds_read_b128 v[178:181], v149
	ds_read_b128 v[182:185], v149 offset:1024
	ds_read_b128 v[186:189], v149 offset:2048
	ds_read_b128 v[190:193], v149 offset:3072
	ds_read_b128 v[202:205], v149 offset:4096
	ds_read_b128 v[206:209], v149 offset:5120
	ds_read_b128 v[220:223], v149 offset:6144
	ds_read_b128 v[224:227], v149 offset:7168
	global_load_lds_dwordx4 v[194:195], off
	v_lshl_add_u64 v[194:195], s[8:9], 0, v[142:143]
	s_add_i32 m0, s82, 0xe000
	s_nop 0
	global_load_lds_dwordx4 v[194:195], off
	s_waitcnt vmcnt(8)
	s_waitcnt lgkmcnt(0)
	s_barrier
	v_mfma_f32_16x16x32_bf16 v[126:129], v[144:147], v[178:181], v[126:129]
	v_mfma_f32_16x16x32_bf16 v[122:125], v[154:157], v[178:181], v[122:125]
	v_mfma_f32_16x16x32_bf16 v[110:113], v[144:147], v[186:189], v[110:113]
	v_mfma_f32_16x16x32_bf16 v[106:109], v[154:157], v[186:189], v[106:109]
	v_mfma_f32_16x16x32_bf16 v[94:97], v[144:147], v[202:205], v[94:97]
	v_mfma_f32_16x16x32_bf16 v[90:93], v[154:157], v[202:205], v[90:93]
	v_mfma_f32_16x16x32_bf16 v[78:81], v[144:147], v[220:223], v[78:81]
	v_mfma_f32_16x16x32_bf16 v[74:77], v[154:157], v[220:223], v[74:77]
	v_mfma_f32_16x16x32_bf16 v[126:129], v[150:153], v[182:185], v[126:129]
	v_mfma_f32_16x16x32_bf16 v[122:125], v[158:161], v[182:185], v[122:125]
	v_mfma_f32_16x16x32_bf16 v[110:113], v[150:153], v[190:193], v[110:113]
	v_mfma_f32_16x16x32_bf16 v[106:109], v[158:161], v[190:193], v[106:109]
	v_mfma_f32_16x16x32_bf16 v[94:97], v[150:153], v[206:209], v[94:97]
	v_mfma_f32_16x16x32_bf16 v[90:93], v[158:161], v[206:209], v[90:93]
	v_mfma_f32_16x16x32_bf16 v[78:81], v[150:153], v[224:227], v[78:81]
	v_mfma_f32_16x16x32_bf16 v[74:77], v[158:161], v[224:227], v[74:77]
	v_mfma_f32_16x16x32_bf16 v[118:121], v[162:165], v[178:181], v[118:121]
	v_mfma_f32_16x16x32_bf16 v[114:117], v[170:173], v[178:181], v[114:117]
	v_mfma_f32_16x16x32_bf16 v[102:105], v[162:165], v[186:189], v[102:105]
	v_mfma_f32_16x16x32_bf16 v[98:101], v[170:173], v[186:189], v[98:101]
	v_mfma_f32_16x16x32_bf16 v[86:89], v[162:165], v[202:205], v[86:89]
	v_mfma_f32_16x16x32_bf16 v[82:85], v[170:173], v[202:205], v[82:85]
	v_mfma_f32_16x16x32_bf16 v[70:73], v[162:165], v[220:223], v[70:73]
	v_mfma_f32_16x16x32_bf16 v[66:69], v[170:173], v[220:223], v[66:69]
	v_mfma_f32_16x16x32_bf16 v[118:121], v[166:169], v[182:185], v[118:121]
	v_mfma_f32_16x16x32_bf16 v[114:117], v[174:177], v[182:185], v[114:117]
	v_mfma_f32_16x16x32_bf16 v[102:105], v[166:169], v[190:193], v[102:105]
	v_mfma_f32_16x16x32_bf16 v[98:101], v[174:177], v[190:193], v[98:101]
	v_mfma_f32_16x16x32_bf16 v[86:89], v[166:169], v[206:209], v[86:89]
	v_mfma_f32_16x16x32_bf16 v[82:85], v[174:177], v[206:209], v[82:85]
	v_mfma_f32_16x16x32_bf16 v[70:73], v[166:169], v[224:227], v[70:73]
	v_mfma_f32_16x16x32_bf16 v[66:69], v[174:177], v[224:227], v[66:69]
	s_barrier
	s_add_i32 s64, s64, s79
	v_lshl_add_u64 v[194:195], s[62:63], 0, v[132:133]
	s_mov_b32 m0, s64
	ds_read_b128 v[178:181], v149 offset:16384
	ds_read_b128 v[182:185], v149 offset:17408
	ds_read_b128 v[186:189], v149 offset:18432
	ds_read_b128 v[190:193], v149 offset:19456
	ds_read_b128 v[202:205], v149 offset:20480
	ds_read_b128 v[206:209], v149 offset:21504
	ds_read_b128 v[220:223], v149 offset:22528
	ds_read_b128 v[224:227], v149 offset:23552
	global_load_lds_dwordx4 v[194:195], off
	s_add_i32 m0, s64, 0x2000
	v_lshl_add_u64 v[198:199], s[62:63], 0, v[136:137]
	s_add_u32 s62, s62, s80
	s_addc_u32 s63, s63, 0
	s_add_i32 s45, s45, s79
	global_load_lds_dwordx4 v[198:199], off
	v_lshl_add_u64 v[200:201], s[62:63], 0, v[132:133]
	s_mov_b32 m0, s45
	v_lshl_add_u64 v[210:211], s[62:63], 0, v[136:137]
	global_load_lds_dwordx4 v[200:201], off
	s_add_i32 m0, s45, 0x2000
	v_lshl_add_u64 v[212:213], s[36:37], 0, v[130:131]
	global_load_lds_dwordx4 v[210:211], off
	s_mov_b32 m0, s82
	v_lshl_add_u64 v[214:215], s[36:37], 0, v[134:135]
	global_load_lds_dwordx4 v[212:213], off
	s_mov_b32 m0, s83
	s_nop 0
	global_load_lds_dwordx4 v[214:215], off
	s_waitcnt vmcnt(8)
	s_waitcnt lgkmcnt(0)
	s_barrier
	v_mfma_f32_16x16x32_bf16 v[62:65], v[144:147], v[178:181], v[62:65]
	v_mfma_f32_16x16x32_bf16 v[58:61], v[154:157], v[178:181], v[58:61]
	v_mfma_f32_16x16x32_bf16 v[46:49], v[144:147], v[186:189], v[46:49]
	v_mfma_f32_16x16x32_bf16 v[42:45], v[154:157], v[186:189], v[42:45]
	v_mfma_f32_16x16x32_bf16 v[30:33], v[144:147], v[202:205], v[30:33]
	v_mfma_f32_16x16x32_bf16 v[26:29], v[154:157], v[202:205], v[26:29]
	v_mfma_f32_16x16x32_bf16 v[14:17], v[144:147], v[220:223], v[14:17]
	v_mfma_f32_16x16x32_bf16 v[10:13], v[154:157], v[220:223], v[10:13]
	v_mfma_f32_16x16x32_bf16 v[62:65], v[150:153], v[182:185], v[62:65]
	v_mfma_f32_16x16x32_bf16 v[58:61], v[158:161], v[182:185], v[58:61]
	v_mfma_f32_16x16x32_bf16 v[46:49], v[150:153], v[190:193], v[46:49]
	v_mfma_f32_16x16x32_bf16 v[42:45], v[158:161], v[190:193], v[42:45]
	v_mfma_f32_16x16x32_bf16 v[30:33], v[150:153], v[206:209], v[30:33]
	v_mfma_f32_16x16x32_bf16 v[26:29], v[158:161], v[206:209], v[26:29]
	v_mfma_f32_16x16x32_bf16 v[14:17], v[150:153], v[224:227], v[14:17]
	v_mfma_f32_16x16x32_bf16 v[10:13], v[158:161], v[224:227], v[10:13]
	v_mfma_f32_16x16x32_bf16 v[54:57], v[162:165], v[178:181], v[54:57]
	v_mfma_f32_16x16x32_bf16 v[50:53], v[170:173], v[178:181], v[50:53]
	v_mfma_f32_16x16x32_bf16 v[38:41], v[162:165], v[186:189], v[38:41]
	v_mfma_f32_16x16x32_bf16 v[34:37], v[170:173], v[186:189], v[34:37]
	v_mfma_f32_16x16x32_bf16 v[22:25], v[162:165], v[202:205], v[22:25]
	v_mfma_f32_16x16x32_bf16 v[18:21], v[170:173], v[202:205], v[18:21]
	v_mfma_f32_16x16x32_bf16 v[6:9], v[162:165], v[220:223], v[6:9]
	v_mfma_f32_16x16x32_bf16 v[2:5], v[170:173], v[220:223], v[2:5]
	v_mfma_f32_16x16x32_bf16 v[54:57], v[166:169], v[182:185], v[54:57]
	v_mfma_f32_16x16x32_bf16 v[50:53], v[174:177], v[182:185], v[50:53]
	v_mfma_f32_16x16x32_bf16 v[38:41], v[166:169], v[190:193], v[38:41]
	v_mfma_f32_16x16x32_bf16 v[34:37], v[174:177], v[190:193], v[34:37]
	v_mfma_f32_16x16x32_bf16 v[22:25], v[166:169], v[206:209], v[22:25]
	v_mfma_f32_16x16x32_bf16 v[18:21], v[174:177], v[206:209], v[18:21]
	v_mfma_f32_16x16x32_bf16 v[6:9], v[166:169], v[224:227], v[6:9]
	v_mfma_f32_16x16x32_bf16 v[2:5], v[174:177], v[224:227], v[2:5]
	s_barrier
	s_add_i32 s45, 0, 0x18000
	s_add_i32 s62, 0, 0x1c000
	v_add_u32_e32 v158, s45, v148
	v_add_u32_e32 v174, s62, v148
	ds_read_b128 v[144:147], v158
	ds_read_b128 v[150:153], v158 offset:1024
	ds_read_b128 v[154:157], v158 offset:2048
	ds_read_b128 v[158:161], v158 offset:3072
	ds_read_b128 v[162:165], v174
	ds_read_b128 v[166:169], v174 offset:1024
	ds_read_b128 v[170:173], v174 offset:2048
	ds_read_b128 v[174:177], v174 offset:3072
	s_add_u32 s36, s36, s80
	s_addc_u32 s37, s37, 0
	s_mov_b32 m0, s86
	v_lshl_add_u64 v[216:217], s[36:37], 0, v[130:131]
	ds_read_b128 v[178:181], v149 offset:32768
	ds_read_b128 v[182:185], v149 offset:33792
	ds_read_b128 v[186:189], v149 offset:34816
	ds_read_b128 v[190:193], v149 offset:35840
	ds_read_b128 v[202:205], v149 offset:36864
	ds_read_b128 v[206:209], v149 offset:37888
	ds_read_b128 v[220:223], v149 offset:38912
	ds_read_b128 v[224:227], v149 offset:39936
	global_load_lds_dwordx4 v[216:217], off
	v_lshl_add_u64 v[216:217], s[36:37], 0, v[134:135]
	s_mov_b32 m0, s87
	s_nop 0
	global_load_lds_dwordx4 v[216:217], off
	s_waitcnt vmcnt(8)
	s_waitcnt lgkmcnt(0)
	s_barrier
	v_mfma_f32_16x16x32_bf16 v[126:129], v[144:147], v[178:181], v[126:129]
	v_mfma_f32_16x16x32_bf16 v[122:125], v[154:157], v[178:181], v[122:125]
	v_mfma_f32_16x16x32_bf16 v[110:113], v[144:147], v[186:189], v[110:113]
	v_mfma_f32_16x16x32_bf16 v[106:109], v[154:157], v[186:189], v[106:109]
	v_mfma_f32_16x16x32_bf16 v[94:97], v[144:147], v[202:205], v[94:97]
	v_mfma_f32_16x16x32_bf16 v[90:93], v[154:157], v[202:205], v[90:93]
	v_mfma_f32_16x16x32_bf16 v[78:81], v[144:147], v[220:223], v[78:81]
	v_mfma_f32_16x16x32_bf16 v[74:77], v[154:157], v[220:223], v[74:77]
	v_mfma_f32_16x16x32_bf16 v[126:129], v[150:153], v[182:185], v[126:129]
	v_mfma_f32_16x16x32_bf16 v[122:125], v[158:161], v[182:185], v[122:125]
	v_mfma_f32_16x16x32_bf16 v[110:113], v[150:153], v[190:193], v[110:113]
	v_mfma_f32_16x16x32_bf16 v[106:109], v[158:161], v[190:193], v[106:109]
	v_mfma_f32_16x16x32_bf16 v[94:97], v[150:153], v[206:209], v[94:97]
	v_mfma_f32_16x16x32_bf16 v[90:93], v[158:161], v[206:209], v[90:93]
	v_mfma_f32_16x16x32_bf16 v[78:81], v[150:153], v[224:227], v[78:81]
	v_mfma_f32_16x16x32_bf16 v[74:77], v[158:161], v[224:227], v[74:77]
	v_mfma_f32_16x16x32_bf16 v[118:121], v[162:165], v[178:181], v[118:121]
	v_mfma_f32_16x16x32_bf16 v[114:117], v[170:173], v[178:181], v[114:117]
	v_mfma_f32_16x16x32_bf16 v[102:105], v[162:165], v[186:189], v[102:105]
	v_mfma_f32_16x16x32_bf16 v[98:101], v[170:173], v[186:189], v[98:101]
	v_mfma_f32_16x16x32_bf16 v[86:89], v[162:165], v[202:205], v[86:89]
	v_mfma_f32_16x16x32_bf16 v[82:85], v[170:173], v[202:205], v[82:85]
	v_mfma_f32_16x16x32_bf16 v[70:73], v[162:165], v[220:223], v[70:73]
	v_mfma_f32_16x16x32_bf16 v[66:69], v[170:173], v[220:223], v[66:69]
	v_mfma_f32_16x16x32_bf16 v[118:121], v[166:169], v[182:185], v[118:121]
	v_mfma_f32_16x16x32_bf16 v[114:117], v[174:177], v[182:185], v[114:117]
	v_mfma_f32_16x16x32_bf16 v[102:105], v[166:169], v[190:193], v[102:105]
	v_mfma_f32_16x16x32_bf16 v[98:101], v[174:177], v[190:193], v[98:101]
	v_mfma_f32_16x16x32_bf16 v[86:89], v[166:169], v[206:209], v[86:89]
	v_mfma_f32_16x16x32_bf16 v[82:85], v[174:177], v[206:209], v[82:85]
	v_mfma_f32_16x16x32_bf16 v[70:73], v[166:169], v[224:227], v[70:73]
	v_mfma_f32_16x16x32_bf16 v[66:69], v[174:177], v[224:227], v[66:69]
	s_barrier
	s_add_i32 s36, s45, s79
	v_lshl_add_u64 v[194:195], v[194:195], 0, s[84:85]
	s_mov_b32 m0, s36
	ds_read_b128 v[178:181], v149 offset:49152
	ds_read_b128 v[182:185], v149 offset:50176
	ds_read_b128 v[186:189], v149 offset:51200
	ds_read_b128 v[190:193], v149 offset:52224
	ds_read_b128 v[202:205], v149 offset:53248
	ds_read_b128 v[206:209], v149 offset:54272
	ds_read_b128 v[220:223], v149 offset:55296
	ds_read_b128 v[224:227], v149 offset:56320
	global_load_lds_dwordx4 v[194:195], off
	v_lshl_add_u64 v[194:195], v[198:199], 0, s[84:85]
	s_add_i32 m0, s36, 0x2000
	s_add_i32 s36, s62, s79
	global_load_lds_dwordx4 v[194:195], off
	v_lshl_add_u64 v[194:195], v[200:201], 0, s[84:85]
	s_mov_b32 m0, s36
	s_nop 0
	global_load_lds_dwordx4 v[194:195], off
	v_lshl_add_u64 v[194:195], v[210:211], 0, s[84:85]
	s_add_i32 m0, s36, 0x2000
	s_nop 0
	global_load_lds_dwordx4 v[194:195], off
	v_lshl_add_u64 v[194:195], v[212:213], 0, s[84:85]
	s_mov_b32 m0, s46
	s_nop 0
	global_load_lds_dwordx4 v[194:195], off
	v_lshl_add_u64 v[194:195], v[214:215], 0, s[84:85]
	s_mov_b32 m0, s47
	s_nop 0
	global_load_lds_dwordx4 v[194:195], off
	s_waitcnt vmcnt(8)
	s_waitcnt lgkmcnt(0)
	s_barrier
	v_mfma_f32_16x16x32_bf16 v[62:65], v[144:147], v[178:181], v[62:65]
	v_mfma_f32_16x16x32_bf16 v[58:61], v[154:157], v[178:181], v[58:61]
	v_mfma_f32_16x16x32_bf16 v[46:49], v[144:147], v[186:189], v[46:49]
	v_mfma_f32_16x16x32_bf16 v[42:45], v[154:157], v[186:189], v[42:45]
	v_mfma_f32_16x16x32_bf16 v[30:33], v[144:147], v[202:205], v[30:33]
	v_mfma_f32_16x16x32_bf16 v[26:29], v[154:157], v[202:205], v[26:29]
	v_mfma_f32_16x16x32_bf16 v[14:17], v[144:147], v[220:223], v[14:17]
	v_mfma_f32_16x16x32_bf16 v[10:13], v[154:157], v[220:223], v[10:13]
	v_mfma_f32_16x16x32_bf16 v[62:65], v[150:153], v[182:185], v[62:65]
	v_mfma_f32_16x16x32_bf16 v[58:61], v[158:161], v[182:185], v[58:61]
	v_mfma_f32_16x16x32_bf16 v[46:49], v[150:153], v[190:193], v[46:49]
	v_mfma_f32_16x16x32_bf16 v[42:45], v[158:161], v[190:193], v[42:45]
	v_mfma_f32_16x16x32_bf16 v[30:33], v[150:153], v[206:209], v[30:33]
	v_mfma_f32_16x16x32_bf16 v[26:29], v[158:161], v[206:209], v[26:29]
	v_mfma_f32_16x16x32_bf16 v[14:17], v[150:153], v[224:227], v[14:17]
	v_mfma_f32_16x16x32_bf16 v[10:13], v[158:161], v[224:227], v[10:13]
	v_mfma_f32_16x16x32_bf16 v[54:57], v[162:165], v[178:181], v[54:57]
	v_mfma_f32_16x16x32_bf16 v[50:53], v[170:173], v[178:181], v[50:53]
	v_mfma_f32_16x16x32_bf16 v[38:41], v[162:165], v[186:189], v[38:41]
	v_mfma_f32_16x16x32_bf16 v[34:37], v[170:173], v[186:189], v[34:37]
	v_mfma_f32_16x16x32_bf16 v[22:25], v[162:165], v[202:205], v[22:25]
	v_mfma_f32_16x16x32_bf16 v[18:21], v[170:173], v[202:205], v[18:21]
	v_mfma_f32_16x16x32_bf16 v[6:9], v[162:165], v[220:223], v[6:9]
	v_mfma_f32_16x16x32_bf16 v[2:5], v[170:173], v[220:223], v[2:5]
	v_mfma_f32_16x16x32_bf16 v[54:57], v[166:169], v[182:185], v[54:57]
	v_mfma_f32_16x16x32_bf16 v[50:53], v[174:177], v[182:185], v[50:53]
	v_mfma_f32_16x16x32_bf16 v[38:41], v[166:169], v[190:193], v[38:41]
	v_mfma_f32_16x16x32_bf16 v[34:37], v[174:177], v[190:193], v[34:37]
	v_mfma_f32_16x16x32_bf16 v[22:25], v[166:169], v[206:209], v[22:25]
	v_mfma_f32_16x16x32_bf16 v[18:21], v[174:177], v[206:209], v[18:21]
	v_mfma_f32_16x16x32_bf16 v[6:9], v[166:169], v[224:227], v[6:9]
	v_mfma_f32_16x16x32_bf16 v[2:5], v[174:177], v[224:227], v[2:5]
	s_barrier
	s_add_u32 s8, s8, 0x100
	s_addc_u32 s9, s9, 0
	s_add_u32 s59, s59, 0x100
	s_addc_u32 s60, s60, 0
	s_cmp_ge_u32 s61, s90
	s_mov_b32 s36, s61
	s_cbranch_scc0 .LBB0_352

.LBB0_438:
	s_add_i32 s58, s36, 2
	s_add_u32 s59, s34, 0x80
	s_addc_u32 s37, s35, 0
	s_add_i32 s62, 0, 0x10000
	s_cmp_eq_u32 s50, s36
	s_cselect_b32 s37, s9, s37
	s_cselect_b32 s36, s8, s59
	v_add_u32_e32 v144, s62, v147
	s_cselect_b32 s61, s21, s57
	s_cselect_b32 s60, s20, s56
	s_add_i32 s59, 0, 0x14000
	ds_read_b128 v[136:139], v144
	ds_read_b128 v[140:143], v144 offset:1024
	ds_read_b128 v[150:153], v144 offset:2048
	ds_read_b128 v[154:157], v144 offset:3072
	v_add_u32_e32 v144, s59, v147
	ds_read_b128 v[158:161], v144
	ds_read_b128 v[162:165], v144 offset:1024
	ds_read_b128 v[166:169], v144 offset:2048
	ds_read_b128 v[170:173], v144 offset:3072
	v_lshl_add_u64 v[144:145], s[34:35], 0, v[132:133]
	s_add_i32 m0, s79, 0xc000
	ds_read_b128 v[174:177], v149
	ds_read_b128 v[178:181], v149 offset:1024
	ds_read_b128 v[182:185], v149 offset:2048
	ds_read_b128 v[186:189], v149 offset:3072
	ds_read_b128 v[190:193], v149 offset:4096
	ds_read_b128 v[202:205], v149 offset:5120
	ds_read_b128 v[206:209], v149 offset:6144
	ds_read_b128 v[220:223], v149 offset:7168
	global_load_lds_dwordx4 v[144:145], off
	v_lshl_add_u64 v[144:145], s[34:35], 0, v[134:135]
	s_add_i32 m0, s79, 0xe000
	s_nop 0
	global_load_lds_dwordx4 v[144:145], off
	s_waitcnt vmcnt(8)
	s_waitcnt lgkmcnt(0)
	s_barrier
	v_mfma_f32_16x16x32_bf16 v[126:129], v[136:139], v[174:177], v[126:129]
	v_mfma_f32_16x16x32_bf16 v[98:101], v[150:153], v[174:177], v[98:101]
	v_mfma_f32_16x16x32_bf16 v[122:125], v[136:139], v[182:185], v[122:125]
	v_mfma_f32_16x16x32_bf16 v[94:97], v[150:153], v[182:185], v[94:97]
	v_mfma_f32_16x16x32_bf16 v[118:121], v[136:139], v[190:193], v[118:121]
	v_mfma_f32_16x16x32_bf16 v[86:89], v[150:153], v[190:193], v[86:89]
	v_mfma_f32_16x16x32_bf16 v[114:117], v[136:139], v[206:209], v[114:117]
	v_mfma_f32_16x16x32_bf16 v[82:85], v[150:153], v[206:209], v[82:85]
	v_mfma_f32_16x16x32_bf16 v[126:129], v[140:143], v[178:181], v[126:129]
	v_mfma_f32_16x16x32_bf16 v[98:101], v[154:157], v[178:181], v[98:101]
	v_mfma_f32_16x16x32_bf16 v[122:125], v[140:143], v[186:189], v[122:125]
	v_mfma_f32_16x16x32_bf16 v[94:97], v[154:157], v[186:189], v[94:97]
	v_mfma_f32_16x16x32_bf16 v[118:121], v[140:143], v[202:205], v[118:121]
	v_mfma_f32_16x16x32_bf16 v[86:89], v[154:157], v[202:205], v[86:89]
	v_mfma_f32_16x16x32_bf16 v[114:117], v[140:143], v[220:223], v[114:117]
	v_mfma_f32_16x16x32_bf16 v[82:85], v[154:157], v[220:223], v[82:85]
	v_mfma_f32_16x16x32_bf16 v[70:73], v[158:161], v[174:177], v[70:73]
	v_mfma_f32_16x16x32_bf16 v[42:45], v[166:169], v[174:177], v[42:45]
	v_mfma_f32_16x16x32_bf16 v[62:65], v[158:161], v[182:185], v[62:65]
	v_mfma_f32_16x16x32_bf16 v[34:37], v[166:169], v[182:185], v[34:37]
	v_mfma_f32_16x16x32_bf16 v[54:57], v[158:161], v[190:193], v[54:57]
	v_mfma_f32_16x16x32_bf16 v[26:29], v[166:169], v[190:193], v[26:29]
	v_mfma_f32_16x16x32_bf16 v[50:53], v[158:161], v[206:209], v[50:53]
	v_mfma_f32_16x16x32_bf16 v[18:21], v[166:169], v[206:209], v[18:21]
	v_mfma_f32_16x16x32_bf16 v[70:73], v[162:165], v[178:181], v[70:73]
	v_mfma_f32_16x16x32_bf16 v[42:45], v[170:173], v[178:181], v[42:45]
	v_mfma_f32_16x16x32_bf16 v[62:65], v[162:165], v[186:189], v[62:65]
	v_mfma_f32_16x16x32_bf16 v[34:37], v[170:173], v[186:189], v[34:37]
	v_mfma_f32_16x16x32_bf16 v[54:57], v[162:165], v[202:205], v[54:57]
	v_mfma_f32_16x16x32_bf16 v[26:29], v[170:173], v[202:205], v[26:29]
	v_mfma_f32_16x16x32_bf16 v[50:53], v[162:165], v[220:223], v[50:53]
	v_mfma_f32_16x16x32_bf16 v[18:21], v[170:173], v[220:223], v[18:21]
	s_barrier
	s_add_i32 s62, s62, s78
	v_lshl_add_u64 v[144:145], s[60:61], 0, v[0:1]
	s_mov_b32 m0, s62
	ds_read_b128 v[174:177], v149 offset:16384
	ds_read_b128 v[178:181], v149 offset:17408
	ds_read_b128 v[182:185], v149 offset:18432
	ds_read_b128 v[186:189], v149 offset:19456
	ds_read_b128 v[190:193], v149 offset:20480
	ds_read_b128 v[202:205], v149 offset:21504
	ds_read_b128 v[206:209], v149 offset:22528
	ds_read_b128 v[220:223], v149 offset:23552
	global_load_lds_dwordx4 v[144:145], off
	s_add_i32 m0, s62, 0x2000
	v_lshl_add_u64 v[194:195], s[60:61], 0, v[130:131]
	s_add_u32 s60, s60, s80
	s_addc_u32 s61, s61, 0
	s_add_i32 s59, s59, s78
	global_load_lds_dwordx4 v[194:195], off
	v_lshl_add_u64 v[198:199], s[60:61], 0, v[0:1]
	s_mov_b32 m0, s59
	v_lshl_add_u64 v[200:201], s[60:61], 0, v[130:131]
	global_load_lds_dwordx4 v[198:199], off
	s_add_i32 m0, s59, 0x2000
	v_lshl_add_u64 v[210:211], s[36:37], 0, v[0:1]
	global_load_lds_dwordx4 v[200:201], off
	s_mov_b32 m0, s79
	v_lshl_add_u64 v[212:213], s[36:37], 0, v[130:131]
	global_load_lds_dwordx4 v[210:211], off
	s_mov_b32 m0, s46
	s_nop 0
	global_load_lds_dwordx4 v[212:213], off
	s_waitcnt vmcnt(8)
	s_waitcnt lgkmcnt(0)
	s_barrier
	v_mfma_f32_16x16x32_bf16 v[110:113], v[136:139], v[174:177], v[110:113]
	v_mfma_f32_16x16x32_bf16 v[78:81], v[150:153], v[174:177], v[78:81]
	v_mfma_f32_16x16x32_bf16 v[106:109], v[136:139], v[182:185], v[106:109]
	v_mfma_f32_16x16x32_bf16 v[74:77], v[150:153], v[182:185], v[74:77]
	v_mfma_f32_16x16x32_bf16 v[102:105], v[136:139], v[190:193], v[102:105]
	v_mfma_f32_16x16x32_bf16 v[66:69], v[150:153], v[190:193], v[66:69]
	v_mfma_f32_16x16x32_bf16 v[90:93], v[136:139], v[206:209], v[90:93]
	v_mfma_f32_16x16x32_bf16 v[58:61], v[150:153], v[206:209], v[58:61]
	v_mfma_f32_16x16x32_bf16 v[110:113], v[140:143], v[178:181], v[110:113]
	v_mfma_f32_16x16x32_bf16 v[78:81], v[154:157], v[178:181], v[78:81]
	v_mfma_f32_16x16x32_bf16 v[106:109], v[140:143], v[186:189], v[106:109]
	v_mfma_f32_16x16x32_bf16 v[74:77], v[154:157], v[186:189], v[74:77]
	v_mfma_f32_16x16x32_bf16 v[102:105], v[140:143], v[202:205], v[102:105]
	v_mfma_f32_16x16x32_bf16 v[66:69], v[154:157], v[202:205], v[66:69]
	v_mfma_f32_16x16x32_bf16 v[90:93], v[140:143], v[220:223], v[90:93]
	v_mfma_f32_16x16x32_bf16 v[58:61], v[154:157], v[220:223], v[58:61]
	v_mfma_f32_16x16x32_bf16 v[46:49], v[158:161], v[174:177], v[46:49]
	v_mfma_f32_16x16x32_bf16 v[14:17], v[166:169], v[174:177], v[14:17]
	v_mfma_f32_16x16x32_bf16 v[38:41], v[158:161], v[182:185], v[38:41]
	v_mfma_f32_16x16x32_bf16 v[10:13], v[166:169], v[182:185], v[10:13]
	v_mfma_f32_16x16x32_bf16 v[30:33], v[158:161], v[190:193], v[30:33]
	v_mfma_f32_16x16x32_bf16 v[6:9], v[166:169], v[190:193], v[6:9]
	v_mfma_f32_16x16x32_bf16 v[22:25], v[158:161], v[206:209], v[22:25]
	v_mfma_f32_16x16x32_bf16 v[2:5], v[166:169], v[206:209], v[2:5]
	v_mfma_f32_16x16x32_bf16 v[46:49], v[162:165], v[178:181], v[46:49]
	v_mfma_f32_16x16x32_bf16 v[14:17], v[170:173], v[178:181], v[14:17]
	v_mfma_f32_16x16x32_bf16 v[38:41], v[162:165], v[186:189], v[38:41]
	v_mfma_f32_16x16x32_bf16 v[10:13], v[170:173], v[186:189], v[10:13]
	v_mfma_f32_16x16x32_bf16 v[30:33], v[162:165], v[202:205], v[30:33]
	v_mfma_f32_16x16x32_bf16 v[6:9], v[170:173], v[202:205], v[6:9]
	v_mfma_f32_16x16x32_bf16 v[22:25], v[162:165], v[220:223], v[22:25]
	v_mfma_f32_16x16x32_bf16 v[2:5], v[170:173], v[220:223], v[2:5]
	s_barrier
	s_add_i32 s59, 0, 0x18000
	s_add_i32 s60, 0, 0x1c000
	v_add_u32_e32 v154, s59, v147
	v_add_u32_e32 v170, s60, v147
	ds_read_b128 v[136:139], v154
	ds_read_b128 v[140:143], v154 offset:1024
	ds_read_b128 v[150:153], v154 offset:2048
	ds_read_b128 v[154:157], v154 offset:3072
	ds_read_b128 v[158:161], v170
	ds_read_b128 v[162:165], v170 offset:1024
	ds_read_b128 v[166:169], v170 offset:2048
	ds_read_b128 v[170:173], v170 offset:3072
	s_add_u32 s36, s36, s80
	s_addc_u32 s37, s37, 0
	s_mov_b32 m0, s47
	v_lshl_add_u64 v[214:215], s[36:37], 0, v[0:1]
	ds_read_b128 v[174:177], v149 offset:32768
	ds_read_b128 v[178:181], v149 offset:33792
	ds_read_b128 v[182:185], v149 offset:34816
	ds_read_b128 v[186:189], v149 offset:35840
	ds_read_b128 v[190:193], v149 offset:36864
	ds_read_b128 v[202:205], v149 offset:37888
	ds_read_b128 v[206:209], v149 offset:38912
	ds_read_b128 v[220:223], v149 offset:39936
	global_load_lds_dwordx4 v[214:215], off
	v_lshl_add_u64 v[214:215], s[36:37], 0, v[130:131]
	s_mov_b32 m0, s82
	s_nop 0
	global_load_lds_dwordx4 v[214:215], off
	s_waitcnt vmcnt(8)
	s_waitcnt lgkmcnt(0)
	s_barrier
	v_mfma_f32_16x16x32_bf16 v[126:129], v[136:139], v[174:177], v[126:129]
	v_mfma_f32_16x16x32_bf16 v[98:101], v[150:153], v[174:177], v[98:101]
	v_mfma_f32_16x16x32_bf16 v[122:125], v[136:139], v[182:185], v[122:125]
	v_mfma_f32_16x16x32_bf16 v[94:97], v[150:153], v[182:185], v[94:97]
	v_mfma_f32_16x16x32_bf16 v[118:121], v[136:139], v[190:193], v[118:121]
	v_mfma_f32_16x16x32_bf16 v[86:89], v[150:153], v[190:193], v[86:89]
	v_mfma_f32_16x16x32_bf16 v[114:117], v[136:139], v[206:209], v[114:117]
	v_mfma_f32_16x16x32_bf16 v[82:85], v[150:153], v[206:209], v[82:85]
	v_mfma_f32_16x16x32_bf16 v[126:129], v[140:143], v[178:181], v[126:129]
	v_mfma_f32_16x16x32_bf16 v[98:101], v[154:157], v[178:181], v[98:101]
	v_mfma_f32_16x16x32_bf16 v[122:125], v[140:143], v[186:189], v[122:125]
	v_mfma_f32_16x16x32_bf16 v[94:97], v[154:157], v[186:189], v[94:97]
	v_mfma_f32_16x16x32_bf16 v[118:121], v[140:143], v[202:205], v[118:121]
	v_mfma_f32_16x16x32_bf16 v[86:89], v[154:157], v[202:205], v[86:89]
	v_mfma_f32_16x16x32_bf16 v[114:117], v[140:143], v[220:223], v[114:117]
	v_mfma_f32_16x16x32_bf16 v[82:85], v[154:157], v[220:223], v[82:85]
	v_mfma_f32_16x16x32_bf16 v[70:73], v[158:161], v[174:177], v[70:73]
	v_mfma_f32_16x16x32_bf16 v[42:45], v[166:169], v[174:177], v[42:45]
	v_mfma_f32_16x16x32_bf16 v[62:65], v[158:161], v[182:185], v[62:65]
	v_mfma_f32_16x16x32_bf16 v[34:37], v[166:169], v[182:185], v[34:37]
	v_mfma_f32_16x16x32_bf16 v[54:57], v[158:161], v[190:193], v[54:57]
	v_mfma_f32_16x16x32_bf16 v[26:29], v[166:169], v[190:193], v[26:29]
	v_mfma_f32_16x16x32_bf16 v[50:53], v[158:161], v[206:209], v[50:53]
	v_mfma_f32_16x16x32_bf16 v[18:21], v[166:169], v[206:209], v[18:21]
	v_mfma_f32_16x16x32_bf16 v[70:73], v[162:165], v[178:181], v[70:73]
	v_mfma_f32_16x16x32_bf16 v[42:45], v[170:173], v[178:181], v[42:45]
	v_mfma_f32_16x16x32_bf16 v[62:65], v[162:165], v[186:189], v[62:65]
	v_mfma_f32_16x16x32_bf16 v[34:37], v[170:173], v[186:189], v[34:37]
	v_mfma_f32_16x16x32_bf16 v[54:57], v[162:165], v[202:205], v[54:57]
	v_mfma_f32_16x16x32_bf16 v[26:29], v[170:173], v[202:205], v[26:29]
	v_mfma_f32_16x16x32_bf16 v[50:53], v[162:165], v[220:223], v[50:53]
	v_mfma_f32_16x16x32_bf16 v[18:21], v[170:173], v[220:223], v[18:21]
	s_barrier
	s_add_i32 s36, s59, s78
	v_lshl_add_u64 v[144:145], v[144:145], 0, s[84:85]
	s_mov_b32 m0, s36
	ds_read_b128 v[174:177], v149 offset:49152
	ds_read_b128 v[178:181], v149 offset:50176
	ds_read_b128 v[182:185], v149 offset:51200
	ds_read_b128 v[186:189], v149 offset:52224
	ds_read_b128 v[190:193], v149 offset:53248
	ds_read_b128 v[202:205], v149 offset:54272
	ds_read_b128 v[206:209], v149 offset:55296
	ds_read_b128 v[220:223], v149 offset:56320
	global_load_lds_dwordx4 v[144:145], off
	v_lshl_add_u64 v[144:145], v[194:195], 0, s[84:85]
	s_add_i32 m0, s36, 0x2000
	s_add_i32 s36, s60, s78
	global_load_lds_dwordx4 v[144:145], off
	v_lshl_add_u64 v[144:145], v[198:199], 0, s[84:85]
	s_mov_b32 m0, s36
	s_nop 0
	global_load_lds_dwordx4 v[144:145], off
	v_lshl_add_u64 v[144:145], v[200:201], 0, s[84:85]
	s_add_i32 m0, s36, 0x2000
	s_nop 0
	global_load_lds_dwordx4 v[144:145], off
	v_lshl_add_u64 v[144:145], v[210:211], 0, s[84:85]
	s_mov_b32 m0, s48
	s_nop 0
	global_load_lds_dwordx4 v[144:145], off
	v_lshl_add_u64 v[144:145], v[212:213], 0, s[84:85]
	s_mov_b32 m0, s49
	s_nop 0
	global_load_lds_dwordx4 v[144:145], off
	s_waitcnt vmcnt(8)
	s_waitcnt lgkmcnt(0)
	s_barrier
	v_mfma_f32_16x16x32_bf16 v[110:113], v[136:139], v[174:177], v[110:113]
	v_mfma_f32_16x16x32_bf16 v[78:81], v[150:153], v[174:177], v[78:81]
	v_mfma_f32_16x16x32_bf16 v[106:109], v[136:139], v[182:185], v[106:109]
	v_mfma_f32_16x16x32_bf16 v[74:77], v[150:153], v[182:185], v[74:77]
	v_mfma_f32_16x16x32_bf16 v[102:105], v[136:139], v[190:193], v[102:105]
	v_mfma_f32_16x16x32_bf16 v[66:69], v[150:153], v[190:193], v[66:69]
	v_mfma_f32_16x16x32_bf16 v[90:93], v[136:139], v[206:209], v[90:93]
	v_mfma_f32_16x16x32_bf16 v[58:61], v[150:153], v[206:209], v[58:61]
	v_mfma_f32_16x16x32_bf16 v[110:113], v[140:143], v[178:181], v[110:113]
	v_mfma_f32_16x16x32_bf16 v[78:81], v[154:157], v[178:181], v[78:81]
	v_mfma_f32_16x16x32_bf16 v[106:109], v[140:143], v[186:189], v[106:109]
	v_mfma_f32_16x16x32_bf16 v[74:77], v[154:157], v[186:189], v[74:77]
	v_mfma_f32_16x16x32_bf16 v[102:105], v[140:143], v[202:205], v[102:105]
	v_mfma_f32_16x16x32_bf16 v[66:69], v[154:157], v[202:205], v[66:69]
	v_mfma_f32_16x16x32_bf16 v[90:93], v[140:143], v[220:223], v[90:93]
	v_mfma_f32_16x16x32_bf16 v[58:61], v[154:157], v[220:223], v[58:61]
	v_mfma_f32_16x16x32_bf16 v[46:49], v[158:161], v[174:177], v[46:49]
	v_mfma_f32_16x16x32_bf16 v[14:17], v[166:169], v[174:177], v[14:17]
	v_mfma_f32_16x16x32_bf16 v[38:41], v[158:161], v[182:185], v[38:41]
	v_mfma_f32_16x16x32_bf16 v[10:13], v[166:169], v[182:185], v[10:13]
	v_mfma_f32_16x16x32_bf16 v[30:33], v[158:161], v[190:193], v[30:33]
	v_mfma_f32_16x16x32_bf16 v[6:9], v[166:169], v[190:193], v[6:9]
	v_mfma_f32_16x16x32_bf16 v[22:25], v[158:161], v[206:209], v[22:25]
	v_mfma_f32_16x16x32_bf16 v[2:5], v[166:169], v[206:209], v[2:5]
	v_mfma_f32_16x16x32_bf16 v[46:49], v[162:165], v[178:181], v[46:49]
	v_mfma_f32_16x16x32_bf16 v[14:17], v[170:173], v[178:181], v[14:17]
	v_mfma_f32_16x16x32_bf16 v[38:41], v[162:165], v[186:189], v[38:41]
	v_mfma_f32_16x16x32_bf16 v[10:13], v[170:173], v[186:189], v[10:13]
	v_mfma_f32_16x16x32_bf16 v[30:33], v[162:165], v[202:205], v[30:33]
	v_mfma_f32_16x16x32_bf16 v[6:9], v[170:173], v[202:205], v[6:9]
	v_mfma_f32_16x16x32_bf16 v[22:25], v[162:165], v[220:223], v[22:25]
	v_mfma_f32_16x16x32_bf16 v[2:5], v[170:173], v[220:223], v[2:5]
	s_barrier
	s_add_u32 s34, s34, 0x100
	s_addc_u32 s35, s35, 0
	s_add_u32 s56, s56, 0x100
	s_addc_u32 s57, s57, 0
	s_cmp_ge_u32 s58, s87
	s_mov_b32 s36, s58
	s_cbranch_scc0 .LBB0_438
	s_and_b64 vcc, exec, s[10:11]
	s_cbranch_vccz .LBB0_441
	s_barrier

.LBB0_483:
	s_add_i32 s61, s38, 2
	s_add_u32 s62, s20, s36
	s_addc_u32 s39, s21, s37
	s_add_u32 s64, s4, s36
	s_addc_u32 s63, s5, s37
	s_add_i32 s65, 0, 0x10000
	s_cmp_eq_u32 s56, s38
	s_cselect_b32 s39, s11, s39
	s_cselect_b32 s38, s10, s62
	v_add_u32_e32 v147, s65, v145
	s_cselect_b32 s63, s35, s63
	s_cselect_b32 s62, s34, s64
	s_add_i32 s64, 0, 0x14000
	ds_read_b128 v[148:151], v147
	ds_read_b128 v[152:155], v147 offset:1024
	ds_read_b128 v[156:159], v147 offset:2048
	ds_read_b128 v[160:163], v147 offset:3072
	v_add_u32_e32 v147, s64, v145
	ds_read_b128 v[164:167], v147
	ds_read_b128 v[168:171], v147 offset:1024
	ds_read_b128 v[172:175], v147 offset:2048
	ds_read_b128 v[176:179], v147 offset:3072
	v_lshl_add_u64 v[194:195], s[20:21], 0, v[142:143]
	s_add_i32 m0, s48, 0xc000
	ds_read_b128 v[180:183], v146
	ds_read_b128 v[184:187], v146 offset:1024
	ds_read_b128 v[190:193], v146 offset:2048
	ds_read_b128 v[202:205], v146 offset:3072
	ds_read_b128 v[206:209], v146 offset:4096
	ds_read_b128 v[220:223], v146 offset:5120
	ds_read_b128 v[224:227], v146 offset:6144
	ds_read_b128 v[228:231], v146 offset:7168
	global_load_lds_dwordx4 v[194:195], off
	v_lshl_add_u64 v[194:195], s[20:21], 0, v[140:141]
	s_add_i32 m0, s48, 0xe000
	s_nop 0
	global_load_lds_dwordx4 v[194:195], off
	s_waitcnt vmcnt(8)
	s_waitcnt lgkmcnt(0)
	s_barrier
	v_mfma_f32_16x16x32_bf16 v[126:129], v[148:151], v[180:183], v[126:129]
	v_mfma_f32_16x16x32_bf16 v[122:125], v[156:159], v[180:183], v[122:125]
	v_mfma_f32_16x16x32_bf16 v[118:121], v[148:151], v[190:193], v[118:121]
	v_mfma_f32_16x16x32_bf16 v[114:117], v[156:159], v[190:193], v[114:117]
	v_mfma_f32_16x16x32_bf16 v[110:113], v[148:151], v[206:209], v[110:113]
	v_mfma_f32_16x16x32_bf16 v[106:109], v[156:159], v[206:209], v[106:109]
	v_mfma_f32_16x16x32_bf16 v[102:105], v[148:151], v[224:227], v[102:105]
	v_mfma_f32_16x16x32_bf16 v[98:101], v[156:159], v[224:227], v[98:101]
	v_mfma_f32_16x16x32_bf16 v[126:129], v[152:155], v[184:187], v[126:129]
	v_mfma_f32_16x16x32_bf16 v[122:125], v[160:163], v[184:187], v[122:125]
	v_mfma_f32_16x16x32_bf16 v[118:121], v[152:155], v[202:205], v[118:121]
	v_mfma_f32_16x16x32_bf16 v[114:117], v[160:163], v[202:205], v[114:117]
	v_mfma_f32_16x16x32_bf16 v[110:113], v[152:155], v[220:223], v[110:113]
	v_mfma_f32_16x16x32_bf16 v[106:109], v[160:163], v[220:223], v[106:109]
	v_mfma_f32_16x16x32_bf16 v[102:105], v[152:155], v[228:231], v[102:105]
	v_mfma_f32_16x16x32_bf16 v[98:101], v[160:163], v[228:231], v[98:101]
	v_mfma_f32_16x16x32_bf16 v[62:65], v[164:167], v[180:183], v[62:65]
	v_mfma_f32_16x16x32_bf16 v[58:61], v[172:175], v[180:183], v[58:61]
	v_mfma_f32_16x16x32_bf16 v[54:57], v[164:167], v[190:193], v[54:57]
	v_mfma_f32_16x16x32_bf16 v[50:53], v[172:175], v[190:193], v[50:53]
	v_mfma_f32_16x16x32_bf16 v[46:49], v[164:167], v[206:209], v[46:49]
	v_mfma_f32_16x16x32_bf16 v[42:45], v[172:175], v[206:209], v[42:45]
	v_mfma_f32_16x16x32_bf16 v[38:41], v[164:167], v[224:227], v[38:41]
	v_mfma_f32_16x16x32_bf16 v[34:37], v[172:175], v[224:227], v[34:37]
	v_mfma_f32_16x16x32_bf16 v[62:65], v[168:171], v[184:187], v[62:65]
	v_mfma_f32_16x16x32_bf16 v[58:61], v[176:179], v[184:187], v[58:61]
	v_mfma_f32_16x16x32_bf16 v[54:57], v[168:171], v[202:205], v[54:57]
	v_mfma_f32_16x16x32_bf16 v[50:53], v[176:179], v[202:205], v[50:53]
	v_mfma_f32_16x16x32_bf16 v[46:49], v[168:171], v[220:223], v[46:49]
	v_mfma_f32_16x16x32_bf16 v[42:45], v[176:179], v[220:223], v[42:45]
	v_mfma_f32_16x16x32_bf16 v[38:41], v[168:171], v[228:231], v[38:41]
	v_mfma_f32_16x16x32_bf16 v[34:37], v[176:179], v[228:231], v[34:37]
	s_barrier
	s_add_i32 s65, s65, s47
	v_lshl_add_u64 v[194:195], s[62:63], 0, v[0:1]
	s_mov_b32 m0, s65
	ds_read_b128 v[180:183], v146 offset:16384
	ds_read_b128 v[184:187], v146 offset:17408
	ds_read_b128 v[190:193], v146 offset:18432
	ds_read_b128 v[202:205], v146 offset:19456
	ds_read_b128 v[206:209], v146 offset:20480
	ds_read_b128 v[220:223], v146 offset:21504
	ds_read_b128 v[224:227], v146 offset:22528
	ds_read_b128 v[228:231], v146 offset:23552
	global_load_lds_dwordx4 v[194:195], off
	s_add_i32 m0, s65, 0x2000
	v_lshl_add_u64 v[198:199], s[62:63], 0, v[134:135]
	s_add_u32 s62, s62, s80
	s_addc_u32 s63, s63, 0
	s_add_i32 s64, s64, s47
	global_load_lds_dwordx4 v[198:199], off
	v_lshl_add_u64 v[200:201], s[62:63], 0, v[0:1]
	s_mov_b32 m0, s64
	v_lshl_add_u64 v[210:211], s[62:63], 0, v[134:135]
	global_load_lds_dwordx4 v[200:201], off
	s_add_i32 m0, s64, 0x2000
	v_lshl_add_u64 v[212:213], s[38:39], 0, v[130:131]
	global_load_lds_dwordx4 v[210:211], off
	s_mov_b32 m0, s48
	v_lshl_add_u64 v[214:215], s[38:39], 0, v[132:133]
	global_load_lds_dwordx4 v[212:213], off
	s_mov_b32 m0, s50
	s_nop 0
	global_load_lds_dwordx4 v[214:215], off
	s_waitcnt vmcnt(8)
	s_waitcnt lgkmcnt(0)
	s_barrier
	v_mfma_f32_16x16x32_bf16 v[94:97], v[148:151], v[180:183], v[94:97]
	v_mfma_f32_16x16x32_bf16 v[90:93], v[156:159], v[180:183], v[90:93]
	v_mfma_f32_16x16x32_bf16 v[86:89], v[148:151], v[190:193], v[86:89]
	v_mfma_f32_16x16x32_bf16 v[82:85], v[156:159], v[190:193], v[82:85]
	v_mfma_f32_16x16x32_bf16 v[78:81], v[148:151], v[206:209], v[78:81]
	v_mfma_f32_16x16x32_bf16 v[74:77], v[156:159], v[206:209], v[74:77]
	v_mfma_f32_16x16x32_bf16 v[70:73], v[148:151], v[224:227], v[70:73]
	v_mfma_f32_16x16x32_bf16 v[66:69], v[156:159], v[224:227], v[66:69]
	v_mfma_f32_16x16x32_bf16 v[94:97], v[152:155], v[184:187], v[94:97]
	v_mfma_f32_16x16x32_bf16 v[90:93], v[160:163], v[184:187], v[90:93]
	v_mfma_f32_16x16x32_bf16 v[86:89], v[152:155], v[202:205], v[86:89]
	v_mfma_f32_16x16x32_bf16 v[82:85], v[160:163], v[202:205], v[82:85]
	v_mfma_f32_16x16x32_bf16 v[78:81], v[152:155], v[220:223], v[78:81]
	v_mfma_f32_16x16x32_bf16 v[74:77], v[160:163], v[220:223], v[74:77]
	v_mfma_f32_16x16x32_bf16 v[70:73], v[152:155], v[228:231], v[70:73]
	v_mfma_f32_16x16x32_bf16 v[66:69], v[160:163], v[228:231], v[66:69]
	v_mfma_f32_16x16x32_bf16 v[30:33], v[164:167], v[180:183], v[30:33]
	v_mfma_f32_16x16x32_bf16 v[26:29], v[172:175], v[180:183], v[26:29]
	v_mfma_f32_16x16x32_bf16 v[22:25], v[164:167], v[190:193], v[22:25]
	v_mfma_f32_16x16x32_bf16 v[18:21], v[172:175], v[190:193], v[18:21]
	v_mfma_f32_16x16x32_bf16 v[14:17], v[164:167], v[206:209], v[14:17]
	v_mfma_f32_16x16x32_bf16 v[10:13], v[172:175], v[206:209], v[10:13]
	v_mfma_f32_16x16x32_bf16 v[6:9], v[164:167], v[224:227], v[6:9]
	v_mfma_f32_16x16x32_bf16 v[2:5], v[172:175], v[224:227], v[2:5]
	v_mfma_f32_16x16x32_bf16 v[30:33], v[168:171], v[184:187], v[30:33]
	v_mfma_f32_16x16x32_bf16 v[26:29], v[176:179], v[184:187], v[26:29]
	v_mfma_f32_16x16x32_bf16 v[22:25], v[168:171], v[202:205], v[22:25]
	v_mfma_f32_16x16x32_bf16 v[18:21], v[176:179], v[202:205], v[18:21]
	v_mfma_f32_16x16x32_bf16 v[14:17], v[168:171], v[220:223], v[14:17]
	v_mfma_f32_16x16x32_bf16 v[10:13], v[176:179], v[220:223], v[10:13]
	v_mfma_f32_16x16x32_bf16 v[6:9], v[168:171], v[228:231], v[6:9]
	v_mfma_f32_16x16x32_bf16 v[2:5], v[176:179], v[228:231], v[2:5]
	s_barrier
	s_add_i32 s62, 0, 0x18000
	v_add_u32_e32 v147, s62, v145
	s_add_i32 s63, 0, 0x1c000
	ds_read_b128 v[148:151], v147
	ds_read_b128 v[152:155], v147 offset:1024
	ds_read_b128 v[156:159], v147 offset:2048
	ds_read_b128 v[160:163], v147 offset:3072
	v_add_u32_e32 v147, s63, v145
	ds_read_b128 v[164:167], v147
	ds_read_b128 v[168:171], v147 offset:1024
	ds_read_b128 v[172:175], v147 offset:2048
	ds_read_b128 v[176:179], v147 offset:3072
	s_add_u32 s38, s38, s80
	s_addc_u32 s39, s39, 0
	s_mov_b32 m0, s51
	v_lshl_add_u64 v[216:217], s[38:39], 0, v[130:131]
	ds_read_b128 v[180:183], v146 offset:32768
	ds_read_b128 v[184:187], v146 offset:33792
	ds_read_b128 v[190:193], v146 offset:34816
	ds_read_b128 v[202:205], v146 offset:35840
	ds_read_b128 v[206:209], v146 offset:36864
	ds_read_b128 v[220:223], v146 offset:37888
	ds_read_b128 v[224:227], v146 offset:38912
	ds_read_b128 v[228:231], v146 offset:39936
	global_load_lds_dwordx4 v[216:217], off
	v_lshl_add_u64 v[216:217], s[38:39], 0, v[132:133]
	s_mov_b32 m0, s52
	s_nop 0
	global_load_lds_dwordx4 v[216:217], off
	s_waitcnt vmcnt(8)
	s_waitcnt lgkmcnt(0)
	s_barrier
	v_mfma_f32_16x16x32_bf16 v[126:129], v[148:151], v[180:183], v[126:129]
	v_mfma_f32_16x16x32_bf16 v[122:125], v[156:159], v[180:183], v[122:125]
	v_mfma_f32_16x16x32_bf16 v[118:121], v[148:151], v[190:193], v[118:121]
	v_mfma_f32_16x16x32_bf16 v[114:117], v[156:159], v[190:193], v[114:117]
	v_mfma_f32_16x16x32_bf16 v[110:113], v[148:151], v[206:209], v[110:113]
	v_mfma_f32_16x16x32_bf16 v[106:109], v[156:159], v[206:209], v[106:109]
	v_mfma_f32_16x16x32_bf16 v[102:105], v[148:151], v[224:227], v[102:105]
	v_mfma_f32_16x16x32_bf16 v[98:101], v[156:159], v[224:227], v[98:101]
	v_mfma_f32_16x16x32_bf16 v[126:129], v[152:155], v[184:187], v[126:129]
	v_mfma_f32_16x16x32_bf16 v[122:125], v[160:163], v[184:187], v[122:125]
	v_mfma_f32_16x16x32_bf16 v[118:121], v[152:155], v[202:205], v[118:121]
	v_mfma_f32_16x16x32_bf16 v[114:117], v[160:163], v[202:205], v[114:117]
	v_mfma_f32_16x16x32_bf16 v[110:113], v[152:155], v[220:223], v[110:113]
	v_mfma_f32_16x16x32_bf16 v[106:109], v[160:163], v[220:223], v[106:109]
	v_mfma_f32_16x16x32_bf16 v[102:105], v[152:155], v[228:231], v[102:105]
	v_mfma_f32_16x16x32_bf16 v[98:101], v[160:163], v[228:231], v[98:101]
	v_mfma_f32_16x16x32_bf16 v[62:65], v[164:167], v[180:183], v[62:65]
	v_mfma_f32_16x16x32_bf16 v[58:61], v[172:175], v[180:183], v[58:61]
	v_mfma_f32_16x16x32_bf16 v[54:57], v[164:167], v[190:193], v[54:57]
	v_mfma_f32_16x16x32_bf16 v[50:53], v[172:175], v[190:193], v[50:53]
	v_mfma_f32_16x16x32_bf16 v[46:49], v[164:167], v[206:209], v[46:49]
	v_mfma_f32_16x16x32_bf16 v[42:45], v[172:175], v[206:209], v[42:45]
	v_mfma_f32_16x16x32_bf16 v[38:41], v[164:167], v[224:227], v[38:41]
	v_mfma_f32_16x16x32_bf16 v[34:37], v[172:175], v[224:227], v[34:37]
	v_mfma_f32_16x16x32_bf16 v[62:65], v[168:171], v[184:187], v[62:65]
	v_mfma_f32_16x16x32_bf16 v[58:61], v[176:179], v[184:187], v[58:61]
	v_mfma_f32_16x16x32_bf16 v[54:57], v[168:171], v[202:205], v[54:57]
	v_mfma_f32_16x16x32_bf16 v[50:53], v[176:179], v[202:205], v[50:53]
	v_mfma_f32_16x16x32_bf16 v[46:49], v[168:171], v[220:223], v[46:49]
	v_mfma_f32_16x16x32_bf16 v[42:45], v[176:179], v[220:223], v[42:45]
	v_mfma_f32_16x16x32_bf16 v[38:41], v[168:171], v[228:231], v[38:41]
	v_mfma_f32_16x16x32_bf16 v[34:37], v[176:179], v[228:231], v[34:37]
	s_barrier
	s_add_i32 s38, s62, s47
	v_lshl_add_u64 v[194:195], v[194:195], 0, s[84:85]
	s_mov_b32 m0, s38
	ds_read_b128 v[180:183], v146 offset:49152
	ds_read_b128 v[184:187], v146 offset:50176
	ds_read_b128 v[190:193], v146 offset:51200
	ds_read_b128 v[202:205], v146 offset:52224
	ds_read_b128 v[206:209], v146 offset:53248
	ds_read_b128 v[220:223], v146 offset:54272
	ds_read_b128 v[224:227], v146 offset:55296
	ds_read_b128 v[228:231], v146 offset:56320
	global_load_lds_dwordx4 v[194:195], off
	v_lshl_add_u64 v[194:195], v[198:199], 0, s[84:85]
	s_add_i32 m0, s38, 0x2000
	s_add_i32 s38, s63, s47
	global_load_lds_dwordx4 v[194:195], off
	v_lshl_add_u64 v[194:195], v[200:201], 0, s[84:85]
	s_mov_b32 m0, s38
	s_nop 0
	global_load_lds_dwordx4 v[194:195], off
	v_lshl_add_u64 v[194:195], v[210:211], 0, s[84:85]
	s_add_i32 m0, s38, 0x2000
	s_nop 0
	global_load_lds_dwordx4 v[194:195], off
	v_lshl_add_u64 v[194:195], v[212:213], 0, s[84:85]
	s_mov_b32 m0, s54
	s_nop 0
	global_load_lds_dwordx4 v[194:195], off
	v_lshl_add_u64 v[194:195], v[214:215], 0, s[84:85]
	s_mov_b32 m0, s55
	s_nop 0
	global_load_lds_dwordx4 v[194:195], off
	s_waitcnt vmcnt(8)
	s_waitcnt lgkmcnt(0)
	s_barrier
	v_mfma_f32_16x16x32_bf16 v[94:97], v[148:151], v[180:183], v[94:97]
	v_mfma_f32_16x16x32_bf16 v[90:93], v[156:159], v[180:183], v[90:93]
	v_mfma_f32_16x16x32_bf16 v[86:89], v[148:151], v[190:193], v[86:89]
	v_mfma_f32_16x16x32_bf16 v[82:85], v[156:159], v[190:193], v[82:85]
	v_mfma_f32_16x16x32_bf16 v[78:81], v[148:151], v[206:209], v[78:81]
	v_mfma_f32_16x16x32_bf16 v[74:77], v[156:159], v[206:209], v[74:77]
	v_mfma_f32_16x16x32_bf16 v[70:73], v[148:151], v[224:227], v[70:73]
	v_mfma_f32_16x16x32_bf16 v[66:69], v[156:159], v[224:227], v[66:69]
	v_mfma_f32_16x16x32_bf16 v[94:97], v[152:155], v[184:187], v[94:97]
	v_mfma_f32_16x16x32_bf16 v[90:93], v[160:163], v[184:187], v[90:93]
	v_mfma_f32_16x16x32_bf16 v[86:89], v[152:155], v[202:205], v[86:89]
	v_mfma_f32_16x16x32_bf16 v[82:85], v[160:163], v[202:205], v[82:85]
	v_mfma_f32_16x16x32_bf16 v[78:81], v[152:155], v[220:223], v[78:81]
	v_mfma_f32_16x16x32_bf16 v[74:77], v[160:163], v[220:223], v[74:77]
	v_mfma_f32_16x16x32_bf16 v[70:73], v[152:155], v[228:231], v[70:73]
	v_mfma_f32_16x16x32_bf16 v[66:69], v[160:163], v[228:231], v[66:69]
	v_mfma_f32_16x16x32_bf16 v[30:33], v[164:167], v[180:183], v[30:33]
	v_mfma_f32_16x16x32_bf16 v[26:29], v[172:175], v[180:183], v[26:29]
	v_mfma_f32_16x16x32_bf16 v[22:25], v[164:167], v[190:193], v[22:25]
	v_mfma_f32_16x16x32_bf16 v[18:21], v[172:175], v[190:193], v[18:21]
	v_mfma_f32_16x16x32_bf16 v[14:17], v[164:167], v[206:209], v[14:17]
	v_mfma_f32_16x16x32_bf16 v[10:13], v[172:175], v[206:209], v[10:13]
	v_mfma_f32_16x16x32_bf16 v[6:9], v[164:167], v[224:227], v[6:9]
	v_mfma_f32_16x16x32_bf16 v[2:5], v[172:175], v[224:227], v[2:5]
	v_mfma_f32_16x16x32_bf16 v[30:33], v[168:171], v[184:187], v[30:33]
	v_mfma_f32_16x16x32_bf16 v[26:29], v[176:179], v[184:187], v[26:29]
	v_mfma_f32_16x16x32_bf16 v[22:25], v[168:171], v[202:205], v[22:25]
	v_mfma_f32_16x16x32_bf16 v[18:21], v[176:179], v[202:205], v[18:21]
	v_mfma_f32_16x16x32_bf16 v[14:17], v[168:171], v[220:223], v[14:17]
	v_mfma_f32_16x16x32_bf16 v[10:13], v[176:179], v[220:223], v[10:13]
	v_mfma_f32_16x16x32_bf16 v[6:9], v[168:171], v[228:231], v[6:9]
	v_mfma_f32_16x16x32_bf16 v[2:5], v[176:179], v[228:231], v[2:5]
	s_barrier
	s_add_u32 s36, s36, 0x100
	s_addc_u32 s37, s37, 0
	v_lshl_add_u64 v[142:143], v[142:143], 0, s[88:89]
	v_lshl_add_u64 v[140:141], v[140:141], 0, s[88:89]
	s_cmp_ge_u32 s61, s53
	s_mov_b32 s38, s61
	s_cbranch_scc0 .LBB0_483
	s_and_b64 vcc, exec, s[8:9]
	s_cbranch_vccnz .LBB0_471
	v_mov_b32_e32 v2, 0
	s_mov_b32 s2, s58
	s_mov_b32 s78, s59
	s_mov_b64 s[4:5], s[34:35]
	s_mov_b64 s[20:21], s[10:11]
	s_mov_b32 s57, s60
	v_mov_b32_e32 v3, v2
	v_mov_b32_e32 v4, v2
	v_mov_b32_e32 v5, v2
	v_mov_b32_e32 v6, v2
	v_mov_b32_e32 v7, v2
	v_mov_b32_e32 v8, v2
	v_mov_b32_e32 v9, v2
	v_mov_b32_e32 v10, v2
	v_mov_b32_e32 v11, v2
	v_mov_b32_e32 v12, v2
	v_mov_b32_e32 v13, v2
	v_mov_b32_e32 v14, v2
	v_mov_b32_e32 v15, v2
	v_mov_b32_e32 v16, v2
	v_mov_b32_e32 v17, v2
	v_mov_b32_e32 v18, v2
	v_mov_b32_e32 v19, v2
	v_mov_b32_e32 v20, v2
	v_mov_b32_e32 v21, v2
	v_mov_b32_e32 v22, v2
	v_mov_b32_e32 v23, v2
	v_mov_b32_e32 v24, v2
	v_mov_b32_e32 v25, v2
	v_mov_b32_e32 v26, v2
	v_mov_b32_e32 v27, v2
	v_mov_b32_e32 v28, v2
	v_mov_b32_e32 v29, v2
	v_mov_b32_e32 v30, v2
	v_mov_b32_e32 v31, v2
	v_mov_b32_e32 v32, v2
	v_mov_b32_e32 v33, v2
	v_mov_b32_e32 v66, v2
	v_mov_b32_e32 v67, v2
	v_mov_b32_e32 v68, v2
	v_mov_b32_e32 v69, v2
	v_mov_b32_e32 v70, v2
	v_mov_b32_e32 v71, v2
	v_mov_b32_e32 v72, v2
	v_mov_b32_e32 v73, v2
	v_mov_b32_e32 v74, v2
	v_mov_b32_e32 v75, v2
	v_mov_b32_e32 v76, v2
	v_mov_b32_e32 v77, v2
	v_mov_b32_e32 v78, v2
	v_mov_b32_e32 v79, v2
	v_mov_b32_e32 v80, v2
	v_mov_b32_e32 v81, v2
	v_mov_b32_e32 v82, v2
	v_mov_b32_e32 v83, v2
	v_mov_b32_e32 v84, v2
	v_mov_b32_e32 v85, v2
	v_mov_b32_e32 v86, v2
	v_mov_b32_e32 v87, v2
	v_mov_b32_e32 v88, v2
	v_mov_b32_e32 v89, v2
	v_mov_b32_e32 v90, v2
	v_mov_b32_e32 v91, v2
	v_mov_b32_e32 v92, v2
	v_mov_b32_e32 v93, v2
	v_mov_b32_e32 v94, v2
	v_mov_b32_e32 v95, v2
	v_mov_b32_e32 v96, v2
	v_mov_b32_e32 v97, v2
	v_mov_b32_e32 v34, v2
	v_mov_b32_e32 v35, v2
	v_mov_b32_e32 v36, v2
	v_mov_b32_e32 v37, v2
	v_mov_b32_e32 v38, v2
	v_mov_b32_e32 v39, v2
	v_mov_b32_e32 v40, v2
	v_mov_b32_e32 v41, v2
	v_mov_b32_e32 v42, v2
	v_mov_b32_e32 v43, v2
	v_mov_b32_e32 v44, v2
	v_mov_b32_e32 v45, v2
	v_mov_b32_e32 v46, v2
	v_mov_b32_e32 v47, v2
	v_mov_b32_e32 v48, v2
	v_mov_b32_e32 v49, v2
	v_mov_b32_e32 v50, v2
	v_mov_b32_e32 v51, v2
	v_mov_b32_e32 v52, v2
	v_mov_b32_e32 v53, v2
	v_mov_b32_e32 v54, v2
	v_mov_b32_e32 v55, v2
	v_mov_b32_e32 v56, v2
	v_mov_b32_e32 v57, v2
	v_mov_b32_e32 v58, v2
	v_mov_b32_e32 v59, v2
	v_mov_b32_e32 v60, v2
	v_mov_b32_e32 v61, v2
	v_mov_b32_e32 v62, v2
	v_mov_b32_e32 v63, v2
	v_mov_b32_e32 v64, v2
	v_mov_b32_e32 v65, v2
	v_mov_b32_e32 v98, v2
	v_mov_b32_e32 v99, v2
	v_mov_b32_e32 v100, v2
	v_mov_b32_e32 v101, v2
	v_mov_b32_e32 v102, v2
	v_mov_b32_e32 v103, v2
	v_mov_b32_e32 v104, v2
	v_mov_b32_e32 v105, v2
	v_mov_b32_e32 v106, v2
	v_mov_b32_e32 v107, v2
	v_mov_b32_e32 v108, v2
	v_mov_b32_e32 v109, v2
	v_mov_b32_e32 v110, v2
	v_mov_b32_e32 v111, v2
	v_mov_b32_e32 v112, v2
	v_mov_b32_e32 v113, v2
	v_mov_b32_e32 v114, v2
	v_mov_b32_e32 v115, v2
	v_mov_b32_e32 v116, v2
	v_mov_b32_e32 v117, v2
	v_mov_b32_e32 v118, v2
	v_mov_b32_e32 v119, v2
	v_mov_b32_e32 v120, v2
	v_mov_b32_e32 v121, v2
	v_mov_b32_e32 v122, v2
	v_mov_b32_e32 v123, v2
	v_mov_b32_e32 v124, v2
	v_mov_b32_e32 v125, v2
	v_mov_b32_e32 v126, v2
	v_mov_b32_e32 v127, v2
	v_mov_b32_e32 v128, v2
	v_mov_b32_e32 v129, v2
	s_branch .LBB0_471

.LBB0_691:
	s_ashr_i32 s15, s14, 31
	s_lshl_b64 s[16:17], s[14:15], 19
	s_add_u32 s16, s82, s16
	s_addc_u32 s17, s83, s17
	s_and_b64 s[18:19], s[6:7], exec
	s_cselect_b32 s15, s17, s5
	s_cselect_b32 s46, s16, s4
	s_ashr_i32 s11, s10, 31
	s_lshl_b64 s[18:19], s[10:11], 19
	s_add_u32 s18, s34, s18
	s_addc_u32 s19, s35, s19
	s_and_b64 s[28:29], s[6:7], exec
	s_cselect_b32 s11, s19, s21
	s_cselect_b32 s47, s18, s20
	s_add_u32 s4, s4, 0x40080
	s_addc_u32 s5, s5, 0
	s_add_u32 s48, s20, 0x100
	s_addc_u32 s49, s21, 0
	s_mov_b32 s50, -2
	s_add_u32 s20, s4, 0xfffc0080
	s_addc_u32 s21, s5, -1
	s_add_i32 s51, 0, 0x10000
	s_cmp_eq_u32 s50, 12
	s_cselect_b32 s29, s15, s21
	s_cselect_b32 s28, s46, s20
	v_add_u32_e32 v140, s51, v143
	s_cselect_b32 s21, s11, s49
	s_cselect_b32 s20, s47, s48
	s_add_i32 s54, 0, 0x14000
	ds_read_b128 v[146:149], v140
	ds_read_b128 v[150:153], v140 offset:1024
	ds_read_b128 v[154:157], v140 offset:2048
	ds_read_b128 v[158:161], v140 offset:3072
	v_add_u32_e32 v140, s54, v143
	ds_read_b128 v[162:165], v140
	ds_read_b128 v[166:169], v140 offset:1024
	ds_read_b128 v[170:173], v140 offset:2048
	ds_read_b128 v[174:177], v140 offset:3072
	v_lshl_add_u64 v[140:141], s[4:5], 0, v[136:137]
	s_add_i32 m0, s38, 0xc000
	ds_read_b128 v[178:181], v145
	ds_read_b128 v[182:185], v145 offset:1024
	ds_read_b128 v[186:189], v145 offset:2048
	ds_read_b128 v[190:193], v145 offset:3072
	ds_read_b128 v[202:205], v145 offset:4096
	ds_read_b128 v[206:209], v145 offset:5120
	ds_read_b128 v[220:223], v145 offset:6144
	ds_read_b128 v[224:227], v145 offset:7168
	global_load_lds_dwordx4 v[140:141], off
	v_lshl_add_u64 v[140:141], s[4:5], 0, v[138:139]
	s_add_i32 m0, s38, 0xe000
	s_nop 0
	global_load_lds_dwordx4 v[140:141], off
	s_waitcnt vmcnt(8)
	s_waitcnt lgkmcnt(0)
	s_barrier
	v_mfma_f32_16x16x32_bf16 v[126:129], v[146:149], v[178:181], 0
	v_mfma_f32_16x16x32_bf16 v[118:121], v[154:157], v[178:181], 0
	v_mfma_f32_16x16x32_bf16 v[110:113], v[146:149], v[186:189], 0
	v_mfma_f32_16x16x32_bf16 v[102:105], v[154:157], v[186:189], 0
	v_mfma_f32_16x16x32_bf16 v[94:97], v[146:149], v[202:205], 0
	v_mfma_f32_16x16x32_bf16 v[86:89], v[154:157], v[202:205], 0
	v_mfma_f32_16x16x32_bf16 v[78:81], v[146:149], v[220:223], 0
	v_mfma_f32_16x16x32_bf16 v[70:73], v[154:157], v[220:223], 0
	v_mfma_f32_16x16x32_bf16 v[126:129], v[150:153], v[182:185], v[126:129]
	v_mfma_f32_16x16x32_bf16 v[118:121], v[158:161], v[182:185], v[118:121]
	v_mfma_f32_16x16x32_bf16 v[110:113], v[150:153], v[190:193], v[110:113]
	v_mfma_f32_16x16x32_bf16 v[102:105], v[158:161], v[190:193], v[102:105]
	v_mfma_f32_16x16x32_bf16 v[94:97], v[150:153], v[206:209], v[94:97]
	v_mfma_f32_16x16x32_bf16 v[86:89], v[158:161], v[206:209], v[86:89]
	v_mfma_f32_16x16x32_bf16 v[78:81], v[150:153], v[224:227], v[78:81]
	v_mfma_f32_16x16x32_bf16 v[70:73], v[158:161], v[224:227], v[70:73]
	v_mfma_f32_16x16x32_bf16 v[122:125], v[162:165], v[178:181], 0
	v_mfma_f32_16x16x32_bf16 v[114:117], v[170:173], v[178:181], 0
	v_mfma_f32_16x16x32_bf16 v[106:109], v[162:165], v[186:189], 0
	v_mfma_f32_16x16x32_bf16 v[98:101], v[170:173], v[186:189], 0
	v_mfma_f32_16x16x32_bf16 v[90:93], v[162:165], v[202:205], 0
	v_mfma_f32_16x16x32_bf16 v[82:85], v[170:173], v[202:205], 0
	v_mfma_f32_16x16x32_bf16 v[74:77], v[162:165], v[220:223], 0
	v_mfma_f32_16x16x32_bf16 v[66:69], v[170:173], v[220:223], 0
	v_mfma_f32_16x16x32_bf16 v[122:125], v[166:169], v[182:185], v[122:125]
	v_mfma_f32_16x16x32_bf16 v[114:117], v[174:177], v[182:185], v[114:117]
	v_mfma_f32_16x16x32_bf16 v[106:109], v[166:169], v[190:193], v[106:109]
	v_mfma_f32_16x16x32_bf16 v[98:101], v[174:177], v[190:193], v[98:101]
	v_mfma_f32_16x16x32_bf16 v[90:93], v[166:169], v[206:209], v[90:93]
	v_mfma_f32_16x16x32_bf16 v[82:85], v[174:177], v[206:209], v[82:85]
	v_mfma_f32_16x16x32_bf16 v[74:77], v[166:169], v[224:227], v[74:77]
	v_mfma_f32_16x16x32_bf16 v[66:69], v[174:177], v[224:227], v[66:69]
	s_barrier
	s_add_i32 s51, s51, s36
	v_lshl_add_u64 v[140:141], s[20:21], 0, v[0:1]
	s_mov_b32 m0, s51
	ds_read_b128 v[178:181], v145 offset:16384
	ds_read_b128 v[182:185], v145 offset:17408
	ds_read_b128 v[186:189], v145 offset:18432
	ds_read_b128 v[190:193], v145 offset:19456
	ds_read_b128 v[202:205], v145 offset:20480
	ds_read_b128 v[206:209], v145 offset:21504
	ds_read_b128 v[220:223], v145 offset:22528
	ds_read_b128 v[224:227], v145 offset:23552
	global_load_lds_dwordx4 v[140:141], off
	s_add_i32 m0, s51, 0x2000
	s_add_u32 s52, s20, 0x40000
	v_lshl_add_u64 v[194:195], s[20:21], 0, v[130:131]
	s_addc_u32 s53, s21, 0
	s_add_i32 s51, s54, s36
	global_load_lds_dwordx4 v[194:195], off
	v_lshl_add_u64 v[198:199], s[52:53], 0, v[0:1]
	s_mov_b32 m0, s51
	v_lshl_add_u64 v[200:201], s[28:29], 0, v[132:133]
	global_load_lds_dwordx4 v[198:199], off
	v_lshl_add_u64 v[198:199], s[52:53], 0, v[130:131]
	s_add_i32 m0, s51, 0x2000
	s_nop 0
	global_load_lds_dwordx4 v[198:199], off
	v_lshl_add_u64 v[198:199], s[28:29], 0, v[134:135]
	s_mov_b32 m0, s38
	s_nop 0
	global_load_lds_dwordx4 v[198:199], off
	s_mov_b32 m0, s39
	s_nop 0
	global_load_lds_dwordx4 v[200:201], off
	s_waitcnt vmcnt(8)
	s_waitcnt lgkmcnt(0)
	s_barrier
	v_mfma_f32_16x16x32_bf16 v[62:65], v[146:149], v[178:181], 0
	v_mfma_f32_16x16x32_bf16 v[54:57], v[154:157], v[178:181], 0
	v_mfma_f32_16x16x32_bf16 v[46:49], v[146:149], v[186:189], 0
	v_mfma_f32_16x16x32_bf16 v[38:41], v[154:157], v[186:189], 0
	v_mfma_f32_16x16x32_bf16 v[30:33], v[146:149], v[202:205], 0
	v_mfma_f32_16x16x32_bf16 v[22:25], v[154:157], v[202:205], 0
	v_mfma_f32_16x16x32_bf16 v[14:17], v[146:149], v[220:223], 0
	v_mfma_f32_16x16x32_bf16 v[6:9], v[154:157], v[220:223], 0
	v_mfma_f32_16x16x32_bf16 v[62:65], v[150:153], v[182:185], v[62:65]
	v_mfma_f32_16x16x32_bf16 v[54:57], v[158:161], v[182:185], v[54:57]
	v_mfma_f32_16x16x32_bf16 v[46:49], v[150:153], v[190:193], v[46:49]
	v_mfma_f32_16x16x32_bf16 v[38:41], v[158:161], v[190:193], v[38:41]
	v_mfma_f32_16x16x32_bf16 v[30:33], v[150:153], v[206:209], v[30:33]
	v_mfma_f32_16x16x32_bf16 v[22:25], v[158:161], v[206:209], v[22:25]
	v_mfma_f32_16x16x32_bf16 v[14:17], v[150:153], v[224:227], v[14:17]
	v_mfma_f32_16x16x32_bf16 v[6:9], v[158:161], v[224:227], v[6:9]
	v_mfma_f32_16x16x32_bf16 v[58:61], v[162:165], v[178:181], 0
	v_mfma_f32_16x16x32_bf16 v[50:53], v[170:173], v[178:181], 0
	v_mfma_f32_16x16x32_bf16 v[42:45], v[162:165], v[186:189], 0
	v_mfma_f32_16x16x32_bf16 v[34:37], v[170:173], v[186:189], 0
	v_mfma_f32_16x16x32_bf16 v[26:29], v[162:165], v[202:205], 0
	v_mfma_f32_16x16x32_bf16 v[18:21], v[170:173], v[202:205], 0
	v_mfma_f32_16x16x32_bf16 v[10:13], v[162:165], v[220:223], 0
	v_mfma_f32_16x16x32_bf16 v[2:5], v[170:173], v[220:223], 0
	v_mfma_f32_16x16x32_bf16 v[58:61], v[166:169], v[182:185], v[58:61]
	v_mfma_f32_16x16x32_bf16 v[50:53], v[174:177], v[182:185], v[50:53]
	v_mfma_f32_16x16x32_bf16 v[42:45], v[166:169], v[190:193], v[42:45]
	v_mfma_f32_16x16x32_bf16 v[34:37], v[174:177], v[190:193], v[34:37]
	v_mfma_f32_16x16x32_bf16 v[26:29], v[166:169], v[206:209], v[26:29]
	v_mfma_f32_16x16x32_bf16 v[18:21], v[174:177], v[206:209], v[18:21]
	v_mfma_f32_16x16x32_bf16 v[10:13], v[166:169], v[224:227], v[10:13]
	v_mfma_f32_16x16x32_bf16 v[2:5], v[174:177], v[224:227], v[2:5]
	s_barrier
	s_add_i32 s51, 0, 0x18000
	s_add_i32 s52, 0, 0x1c000
	v_add_u32_e32 v158, s51, v143
	v_add_u32_e32 v174, s52, v143
	ds_read_b128 v[146:149], v158
	ds_read_b128 v[150:153], v158 offset:1024
	ds_read_b128 v[154:157], v158 offset:2048
	ds_read_b128 v[158:161], v158 offset:3072
	ds_read_b128 v[162:165], v174
	ds_read_b128 v[166:169], v174 offset:1024
	ds_read_b128 v[170:173], v174 offset:2048
	ds_read_b128 v[174:177], v174 offset:3072
	s_add_u32 s28, s28, 0x40000
	s_addc_u32 s29, s29, 0
	s_mov_b32 m0, s40
	v_lshl_add_u64 v[210:211], s[28:29], 0, v[134:135]
	ds_read_b128 v[178:181], v145 offset:32768
	ds_read_b128 v[182:185], v145 offset:33792
	ds_read_b128 v[186:189], v145 offset:34816
	ds_read_b128 v[190:193], v145 offset:35840
	ds_read_b128 v[202:205], v145 offset:36864
	ds_read_b128 v[206:209], v145 offset:37888
	ds_read_b128 v[220:223], v145 offset:38912
	ds_read_b128 v[224:227], v145 offset:39936
	global_load_lds_dwordx4 v[210:211], off
	v_lshl_add_u64 v[210:211], s[28:29], 0, v[132:133]
	s_mov_b32 m0, s41
	s_nop 0
	global_load_lds_dwordx4 v[210:211], off
	s_waitcnt vmcnt(8)
	s_waitcnt lgkmcnt(0)
	s_barrier
	v_mfma_f32_16x16x32_bf16 v[126:129], v[146:149], v[178:181], v[126:129]
	v_mfma_f32_16x16x32_bf16 v[118:121], v[154:157], v[178:181], v[118:121]
	v_mfma_f32_16x16x32_bf16 v[110:113], v[146:149], v[186:189], v[110:113]
	v_mfma_f32_16x16x32_bf16 v[102:105], v[154:157], v[186:189], v[102:105]
	v_mfma_f32_16x16x32_bf16 v[94:97], v[146:149], v[202:205], v[94:97]
	v_mfma_f32_16x16x32_bf16 v[86:89], v[154:157], v[202:205], v[86:89]
	v_mfma_f32_16x16x32_bf16 v[78:81], v[146:149], v[220:223], v[78:81]
	v_mfma_f32_16x16x32_bf16 v[70:73], v[154:157], v[220:223], v[70:73]
	v_mfma_f32_16x16x32_bf16 v[126:129], v[150:153], v[182:185], v[126:129]
	v_mfma_f32_16x16x32_bf16 v[118:121], v[158:161], v[182:185], v[118:121]
	v_mfma_f32_16x16x32_bf16 v[110:113], v[150:153], v[190:193], v[110:113]
	v_mfma_f32_16x16x32_bf16 v[102:105], v[158:161], v[190:193], v[102:105]
	v_mfma_f32_16x16x32_bf16 v[94:97], v[150:153], v[206:209], v[94:97]
	v_mfma_f32_16x16x32_bf16 v[86:89], v[158:161], v[206:209], v[86:89]
	v_mfma_f32_16x16x32_bf16 v[78:81], v[150:153], v[224:227], v[78:81]
	v_mfma_f32_16x16x32_bf16 v[70:73], v[158:161], v[224:227], v[70:73]
	v_mfma_f32_16x16x32_bf16 v[122:125], v[162:165], v[178:181], v[122:125]
	v_mfma_f32_16x16x32_bf16 v[114:117], v[170:173], v[178:181], v[114:117]
	v_mfma_f32_16x16x32_bf16 v[106:109], v[162:165], v[186:189], v[106:109]
	v_mfma_f32_16x16x32_bf16 v[98:101], v[170:173], v[186:189], v[98:101]
	v_mfma_f32_16x16x32_bf16 v[90:93], v[162:165], v[202:205], v[90:93]
	v_mfma_f32_16x16x32_bf16 v[82:85], v[170:173], v[202:205], v[82:85]
	v_mfma_f32_16x16x32_bf16 v[74:77], v[162:165], v[220:223], v[74:77]
	v_mfma_f32_16x16x32_bf16 v[66:69], v[170:173], v[220:223], v[66:69]
	v_mfma_f32_16x16x32_bf16 v[122:125], v[166:169], v[182:185], v[122:125]
	v_mfma_f32_16x16x32_bf16 v[114:117], v[174:177], v[182:185], v[114:117]
	v_mfma_f32_16x16x32_bf16 v[106:109], v[166:169], v[190:193], v[106:109]
	v_mfma_f32_16x16x32_bf16 v[98:101], v[174:177], v[190:193], v[98:101]
	v_mfma_f32_16x16x32_bf16 v[90:93], v[166:169], v[206:209], v[90:93]
	v_mfma_f32_16x16x32_bf16 v[82:85], v[174:177], v[206:209], v[82:85]
	v_mfma_f32_16x16x32_bf16 v[74:77], v[166:169], v[224:227], v[74:77]
	v_mfma_f32_16x16x32_bf16 v[66:69], v[174:177], v[224:227], v[66:69]
	s_barrier
	s_add_i32 s28, s51, s36
	v_lshl_add_u64 v[140:141], v[140:141], 0, s[84:85]
	s_mov_b32 m0, s28
	ds_read_b128 v[178:181], v145 offset:49152
	ds_read_b128 v[182:185], v145 offset:50176
	ds_read_b128 v[186:189], v145 offset:51200
	ds_read_b128 v[190:193], v145 offset:52224
	ds_read_b128 v[202:205], v145 offset:53248
	ds_read_b128 v[206:209], v145 offset:54272
	ds_read_b128 v[220:223], v145 offset:55296
	ds_read_b128 v[224:227], v145 offset:56320
	global_load_lds_dwordx4 v[140:141], off
	s_add_i32 m0, s28, 0x2000
	s_add_u32 s20, s20, 0x40080
	v_lshl_add_u64 v[140:141], v[194:195], 0, s[84:85]
	s_addc_u32 s21, s21, 0
	s_add_i32 s28, s52, s36
	global_load_lds_dwordx4 v[140:141], off
	v_lshl_add_u64 v[140:141], s[20:21], 0, v[0:1]
	s_mov_b32 m0, s28
	s_nop 0
	global_load_lds_dwordx4 v[140:141], off
	v_lshl_add_u64 v[140:141], s[20:21], 0, v[130:131]
	s_add_i32 m0, s28, 0x2000
	s_nop 0
	global_load_lds_dwordx4 v[140:141], off
	v_lshl_add_u64 v[140:141], v[198:199], 0, s[84:85]
	s_mov_b32 m0, s76
	s_nop 0
	global_load_lds_dwordx4 v[140:141], off
	v_lshl_add_u64 v[140:141], v[200:201], 0, s[84:85]
	s_mov_b32 m0, s77
	s_nop 0
	global_load_lds_dwordx4 v[140:141], off
	s_waitcnt vmcnt(8)
	s_waitcnt lgkmcnt(0)
	s_barrier
	v_mfma_f32_16x16x32_bf16 v[62:65], v[146:149], v[178:181], v[62:65]
	v_mfma_f32_16x16x32_bf16 v[54:57], v[154:157], v[178:181], v[54:57]
	v_mfma_f32_16x16x32_bf16 v[46:49], v[146:149], v[186:189], v[46:49]
	v_mfma_f32_16x16x32_bf16 v[38:41], v[154:157], v[186:189], v[38:41]
	v_mfma_f32_16x16x32_bf16 v[30:33], v[146:149], v[202:205], v[30:33]
	v_mfma_f32_16x16x32_bf16 v[22:25], v[154:157], v[202:205], v[22:25]
	v_mfma_f32_16x16x32_bf16 v[14:17], v[146:149], v[220:223], v[14:17]
	v_mfma_f32_16x16x32_bf16 v[6:9], v[154:157], v[220:223], v[6:9]
	v_mfma_f32_16x16x32_bf16 v[62:65], v[150:153], v[182:185], v[62:65]
	v_mfma_f32_16x16x32_bf16 v[54:57], v[158:161], v[182:185], v[54:57]
	v_mfma_f32_16x16x32_bf16 v[46:49], v[150:153], v[190:193], v[46:49]
	v_mfma_f32_16x16x32_bf16 v[38:41], v[158:161], v[190:193], v[38:41]
	v_mfma_f32_16x16x32_bf16 v[30:33], v[150:153], v[206:209], v[30:33]
	v_mfma_f32_16x16x32_bf16 v[22:25], v[158:161], v[206:209], v[22:25]
	v_mfma_f32_16x16x32_bf16 v[14:17], v[150:153], v[224:227], v[14:17]
	v_mfma_f32_16x16x32_bf16 v[6:9], v[158:161], v[224:227], v[6:9]
	v_mfma_f32_16x16x32_bf16 v[58:61], v[162:165], v[178:181], v[58:61]
	v_mfma_f32_16x16x32_bf16 v[50:53], v[170:173], v[178:181], v[50:53]
	v_mfma_f32_16x16x32_bf16 v[42:45], v[162:165], v[186:189], v[42:45]
	v_mfma_f32_16x16x32_bf16 v[34:37], v[170:173], v[186:189], v[34:37]
	v_mfma_f32_16x16x32_bf16 v[26:29], v[162:165], v[202:205], v[26:29]
	v_mfma_f32_16x16x32_bf16 v[18:21], v[170:173], v[202:205], v[18:21]
	v_mfma_f32_16x16x32_bf16 v[10:13], v[162:165], v[220:223], v[10:13]
	v_mfma_f32_16x16x32_bf16 v[2:5], v[170:173], v[220:223], v[2:5]
	v_mfma_f32_16x16x32_bf16 v[58:61], v[166:169], v[182:185], v[58:61]
	v_mfma_f32_16x16x32_bf16 v[50:53], v[174:177], v[182:185], v[50:53]
	v_mfma_f32_16x16x32_bf16 v[42:45], v[166:169], v[190:193], v[42:45]
	v_mfma_f32_16x16x32_bf16 v[34:37], v[174:177], v[190:193], v[34:37]
	v_mfma_f32_16x16x32_bf16 v[26:29], v[166:169], v[206:209], v[26:29]
	v_mfma_f32_16x16x32_bf16 v[18:21], v[174:177], v[206:209], v[18:21]
	v_mfma_f32_16x16x32_bf16 v[10:13], v[166:169], v[224:227], v[10:13]
	v_mfma_f32_16x16x32_bf16 v[2:5], v[174:177], v[224:227], v[2:5]
	s_barrier
	s_add_i32 s50, s50, 2
	s_add_u32 s4, s4, 0x100
	s_addc_u32 s5, s5, 0
	s_add_u32 s48, s48, 0x100
	s_addc_u32 s49, s49, 0
	s_cmp_gt_u32 s50, 13
	s_cbranch_scc1 .Lpeel_exit_swi
.LBB0_692:
	s_add_u32 s20, s4, 0xfffc0080
	s_addc_u32 s21, s5, -1
	s_add_i32 s51, 0, 0x10000
	s_cmp_eq_u32 s50, 12
	s_cselect_b32 s29, s15, s21
	s_cselect_b32 s28, s46, s20
	v_add_u32_e32 v140, s51, v143
	s_cselect_b32 s21, s11, s49
	s_cselect_b32 s20, s47, s48
	s_add_i32 s54, 0, 0x14000
	ds_read_b128 v[146:149], v140
	ds_read_b128 v[150:153], v140 offset:1024
	ds_read_b128 v[154:157], v140 offset:2048
	ds_read_b128 v[158:161], v140 offset:3072
	v_add_u32_e32 v140, s54, v143
	ds_read_b128 v[162:165], v140
	ds_read_b128 v[166:169], v140 offset:1024
	ds_read_b128 v[170:173], v140 offset:2048
	ds_read_b128 v[174:177], v140 offset:3072
	v_lshl_add_u64 v[140:141], s[4:5], 0, v[136:137]
	s_add_i32 m0, s38, 0xc000
	ds_read_b128 v[178:181], v145
	ds_read_b128 v[182:185], v145 offset:1024
	ds_read_b128 v[186:189], v145 offset:2048
	ds_read_b128 v[190:193], v145 offset:3072
	ds_read_b128 v[202:205], v145 offset:4096
	ds_read_b128 v[206:209], v145 offset:5120
	ds_read_b128 v[220:223], v145 offset:6144
	ds_read_b128 v[224:227], v145 offset:7168
	global_load_lds_dwordx4 v[140:141], off
	v_lshl_add_u64 v[140:141], s[4:5], 0, v[138:139]
	s_add_i32 m0, s38, 0xe000
	s_nop 0
	global_load_lds_dwordx4 v[140:141], off
	s_waitcnt vmcnt(8)
	s_waitcnt lgkmcnt(0)
	s_barrier
	v_mfma_f32_16x16x32_bf16 v[126:129], v[146:149], v[178:181], v[126:129]
	v_mfma_f32_16x16x32_bf16 v[118:121], v[154:157], v[178:181], v[118:121]
	v_mfma_f32_16x16x32_bf16 v[110:113], v[146:149], v[186:189], v[110:113]
	v_mfma_f32_16x16x32_bf16 v[102:105], v[154:157], v[186:189], v[102:105]
	v_mfma_f32_16x16x32_bf16 v[94:97], v[146:149], v[202:205], v[94:97]
	v_mfma_f32_16x16x32_bf16 v[86:89], v[154:157], v[202:205], v[86:89]
	v_mfma_f32_16x16x32_bf16 v[78:81], v[146:149], v[220:223], v[78:81]
	v_mfma_f32_16x16x32_bf16 v[70:73], v[154:157], v[220:223], v[70:73]
	v_mfma_f32_16x16x32_bf16 v[126:129], v[150:153], v[182:185], v[126:129]
	v_mfma_f32_16x16x32_bf16 v[118:121], v[158:161], v[182:185], v[118:121]
	v_mfma_f32_16x16x32_bf16 v[110:113], v[150:153], v[190:193], v[110:113]
	v_mfma_f32_16x16x32_bf16 v[102:105], v[158:161], v[190:193], v[102:105]
	v_mfma_f32_16x16x32_bf16 v[94:97], v[150:153], v[206:209], v[94:97]
	v_mfma_f32_16x16x32_bf16 v[86:89], v[158:161], v[206:209], v[86:89]
	v_mfma_f32_16x16x32_bf16 v[78:81], v[150:153], v[224:227], v[78:81]
	v_mfma_f32_16x16x32_bf16 v[70:73], v[158:161], v[224:227], v[70:73]
	v_mfma_f32_16x16x32_bf16 v[122:125], v[162:165], v[178:181], v[122:125]
	v_mfma_f32_16x16x32_bf16 v[114:117], v[170:173], v[178:181], v[114:117]
	v_mfma_f32_16x16x32_bf16 v[106:109], v[162:165], v[186:189], v[106:109]
	v_mfma_f32_16x16x32_bf16 v[98:101], v[170:173], v[186:189], v[98:101]
	v_mfma_f32_16x16x32_bf16 v[90:93], v[162:165], v[202:205], v[90:93]
	v_mfma_f32_16x16x32_bf16 v[82:85], v[170:173], v[202:205], v[82:85]
	v_mfma_f32_16x16x32_bf16 v[74:77], v[162:165], v[220:223], v[74:77]
	v_mfma_f32_16x16x32_bf16 v[66:69], v[170:173], v[220:223], v[66:69]
	v_mfma_f32_16x16x32_bf16 v[122:125], v[166:169], v[182:185], v[122:125]
	v_mfma_f32_16x16x32_bf16 v[114:117], v[174:177], v[182:185], v[114:117]
	v_mfma_f32_16x16x32_bf16 v[106:109], v[166:169], v[190:193], v[106:109]
	v_mfma_f32_16x16x32_bf16 v[98:101], v[174:177], v[190:193], v[98:101]
	v_mfma_f32_16x16x32_bf16 v[90:93], v[166:169], v[206:209], v[90:93]
	v_mfma_f32_16x16x32_bf16 v[82:85], v[174:177], v[206:209], v[82:85]
	v_mfma_f32_16x16x32_bf16 v[74:77], v[166:169], v[224:227], v[74:77]
	v_mfma_f32_16x16x32_bf16 v[66:69], v[174:177], v[224:227], v[66:69]
	s_barrier
	s_add_i32 s51, s51, s36
	v_lshl_add_u64 v[140:141], s[20:21], 0, v[0:1]
	s_mov_b32 m0, s51
	ds_read_b128 v[178:181], v145 offset:16384
	ds_read_b128 v[182:185], v145 offset:17408
	ds_read_b128 v[186:189], v145 offset:18432
	ds_read_b128 v[190:193], v145 offset:19456
	ds_read_b128 v[202:205], v145 offset:20480
	ds_read_b128 v[206:209], v145 offset:21504
	ds_read_b128 v[220:223], v145 offset:22528
	ds_read_b128 v[224:227], v145 offset:23552
	global_load_lds_dwordx4 v[140:141], off
	s_add_i32 m0, s51, 0x2000
	s_add_u32 s52, s20, 0x40000
	v_lshl_add_u64 v[194:195], s[20:21], 0, v[130:131]
	s_addc_u32 s53, s21, 0
	s_add_i32 s51, s54, s36
	global_load_lds_dwordx4 v[194:195], off
	v_lshl_add_u64 v[198:199], s[52:53], 0, v[0:1]
	s_mov_b32 m0, s51
	v_lshl_add_u64 v[200:201], s[28:29], 0, v[132:133]
	global_load_lds_dwordx4 v[198:199], off
	v_lshl_add_u64 v[198:199], s[52:53], 0, v[130:131]
	s_add_i32 m0, s51, 0x2000
	s_nop 0
	global_load_lds_dwordx4 v[198:199], off
	v_lshl_add_u64 v[198:199], s[28:29], 0, v[134:135]
	s_mov_b32 m0, s38
	s_nop 0
	global_load_lds_dwordx4 v[198:199], off
	s_mov_b32 m0, s39
	s_nop 0
	global_load_lds_dwordx4 v[200:201], off
	s_waitcnt vmcnt(8)
	s_waitcnt lgkmcnt(0)
	s_barrier
	v_mfma_f32_16x16x32_bf16 v[62:65], v[146:149], v[178:181], v[62:65]
	v_mfma_f32_16x16x32_bf16 v[54:57], v[154:157], v[178:181], v[54:57]
	v_mfma_f32_16x16x32_bf16 v[46:49], v[146:149], v[186:189], v[46:49]
	v_mfma_f32_16x16x32_bf16 v[38:41], v[154:157], v[186:189], v[38:41]
	v_mfma_f32_16x16x32_bf16 v[30:33], v[146:149], v[202:205], v[30:33]
	v_mfma_f32_16x16x32_bf16 v[22:25], v[154:157], v[202:205], v[22:25]
	v_mfma_f32_16x16x32_bf16 v[14:17], v[146:149], v[220:223], v[14:17]
	v_mfma_f32_16x16x32_bf16 v[6:9], v[154:157], v[220:223], v[6:9]
	v_mfma_f32_16x16x32_bf16 v[62:65], v[150:153], v[182:185], v[62:65]
	v_mfma_f32_16x16x32_bf16 v[54:57], v[158:161], v[182:185], v[54:57]
	v_mfma_f32_16x16x32_bf16 v[46:49], v[150:153], v[190:193], v[46:49]
	v_mfma_f32_16x16x32_bf16 v[38:41], v[158:161], v[190:193], v[38:41]
	v_mfma_f32_16x16x32_bf16 v[30:33], v[150:153], v[206:209], v[30:33]
	v_mfma_f32_16x16x32_bf16 v[22:25], v[158:161], v[206:209], v[22:25]
	v_mfma_f32_16x16x32_bf16 v[14:17], v[150:153], v[224:227], v[14:17]
	v_mfma_f32_16x16x32_bf16 v[6:9], v[158:161], v[224:227], v[6:9]
	v_mfma_f32_16x16x32_bf16 v[58:61], v[162:165], v[178:181], v[58:61]
	v_mfma_f32_16x16x32_bf16 v[50:53], v[170:173], v[178:181], v[50:53]
	v_mfma_f32_16x16x32_bf16 v[42:45], v[162:165], v[186:189], v[42:45]
	v_mfma_f32_16x16x32_bf16 v[34:37], v[170:173], v[186:189], v[34:37]
	v_mfma_f32_16x16x32_bf16 v[26:29], v[162:165], v[202:205], v[26:29]
	v_mfma_f32_16x16x32_bf16 v[18:21], v[170:173], v[202:205], v[18:21]
	v_mfma_f32_16x16x32_bf16 v[10:13], v[162:165], v[220:223], v[10:13]
	v_mfma_f32_16x16x32_bf16 v[2:5], v[170:173], v[220:223], v[2:5]
	v_mfma_f32_16x16x32_bf16 v[58:61], v[166:169], v[182:185], v[58:61]
	v_mfma_f32_16x16x32_bf16 v[50:53], v[174:177], v[182:185], v[50:53]
	v_mfma_f32_16x16x32_bf16 v[42:45], v[166:169], v[190:193], v[42:45]
	v_mfma_f32_16x16x32_bf16 v[34:37], v[174:177], v[190:193], v[34:37]
	v_mfma_f32_16x16x32_bf16 v[26:29], v[166:169], v[206:209], v[26:29]
	v_mfma_f32_16x16x32_bf16 v[18:21], v[174:177], v[206:209], v[18:21]
	v_mfma_f32_16x16x32_bf16 v[10:13], v[166:169], v[224:227], v[10:13]
	v_mfma_f32_16x16x32_bf16 v[2:5], v[174:177], v[224:227], v[2:5]
	s_barrier
	s_add_i32 s51, 0, 0x18000
	s_add_i32 s52, 0, 0x1c000
	v_add_u32_e32 v158, s51, v143
	v_add_u32_e32 v174, s52, v143
	ds_read_b128 v[146:149], v158
	ds_read_b128 v[150:153], v158 offset:1024
	ds_read_b128 v[154:157], v158 offset:2048
	ds_read_b128 v[158:161], v158 offset:3072
	ds_read_b128 v[162:165], v174
	ds_read_b128 v[166:169], v174 offset:1024
	ds_read_b128 v[170:173], v174 offset:2048
	ds_read_b128 v[174:177], v174 offset:3072
	s_add_u32 s28, s28, 0x40000
	s_addc_u32 s29, s29, 0
	s_mov_b32 m0, s40
	v_lshl_add_u64 v[210:211], s[28:29], 0, v[134:135]
	ds_read_b128 v[178:181], v145 offset:32768
	ds_read_b128 v[182:185], v145 offset:33792
	ds_read_b128 v[186:189], v145 offset:34816
	ds_read_b128 v[190:193], v145 offset:35840
	ds_read_b128 v[202:205], v145 offset:36864
	ds_read_b128 v[206:209], v145 offset:37888
	ds_read_b128 v[220:223], v145 offset:38912
	ds_read_b128 v[224:227], v145 offset:39936
	global_load_lds_dwordx4 v[210:211], off
	v_lshl_add_u64 v[210:211], s[28:29], 0, v[132:133]
	s_mov_b32 m0, s41
	s_nop 0
	global_load_lds_dwordx4 v[210:211], off
	s_waitcnt vmcnt(8)
	s_waitcnt lgkmcnt(0)
	s_barrier
	v_mfma_f32_16x16x32_bf16 v[126:129], v[146:149], v[178:181], v[126:129]
	v_mfma_f32_16x16x32_bf16 v[118:121], v[154:157], v[178:181], v[118:121]
	v_mfma_f32_16x16x32_bf16 v[110:113], v[146:149], v[186:189], v[110:113]
	v_mfma_f32_16x16x32_bf16 v[102:105], v[154:157], v[186:189], v[102:105]
	v_mfma_f32_16x16x32_bf16 v[94:97], v[146:149], v[202:205], v[94:97]
	v_mfma_f32_16x16x32_bf16 v[86:89], v[154:157], v[202:205], v[86:89]
	v_mfma_f32_16x16x32_bf16 v[78:81], v[146:149], v[220:223], v[78:81]
	v_mfma_f32_16x16x32_bf16 v[70:73], v[154:157], v[220:223], v[70:73]
	v_mfma_f32_16x16x32_bf16 v[126:129], v[150:153], v[182:185], v[126:129]
	v_mfma_f32_16x16x32_bf16 v[118:121], v[158:161], v[182:185], v[118:121]
	v_mfma_f32_16x16x32_bf16 v[110:113], v[150:153], v[190:193], v[110:113]
	v_mfma_f32_16x16x32_bf16 v[102:105], v[158:161], v[190:193], v[102:105]
	v_mfma_f32_16x16x32_bf16 v[94:97], v[150:153], v[206:209], v[94:97]
	v_mfma_f32_16x16x32_bf16 v[86:89], v[158:161], v[206:209], v[86:89]
	v_mfma_f32_16x16x32_bf16 v[78:81], v[150:153], v[224:227], v[78:81]
	v_mfma_f32_16x16x32_bf16 v[70:73], v[158:161], v[224:227], v[70:73]
	v_mfma_f32_16x16x32_bf16 v[122:125], v[162:165], v[178:181], v[122:125]
	v_mfma_f32_16x16x32_bf16 v[114:117], v[170:173], v[178:181], v[114:117]
	v_mfma_f32_16x16x32_bf16 v[106:109], v[162:165], v[186:189], v[106:109]
	v_mfma_f32_16x16x32_bf16 v[98:101], v[170:173], v[186:189], v[98:101]
	v_mfma_f32_16x16x32_bf16 v[90:93], v[162:165], v[202:205], v[90:93]
	v_mfma_f32_16x16x32_bf16 v[82:85], v[170:173], v[202:205], v[82:85]
	v_mfma_f32_16x16x32_bf16 v[74:77], v[162:165], v[220:223], v[74:77]
	v_mfma_f32_16x16x32_bf16 v[66:69], v[170:173], v[220:223], v[66:69]
	v_mfma_f32_16x16x32_bf16 v[122:125], v[166:169], v[182:185], v[122:125]
	v_mfma_f32_16x16x32_bf16 v[114:117], v[174:177], v[182:185], v[114:117]
	v_mfma_f32_16x16x32_bf16 v[106:109], v[166:169], v[190:193], v[106:109]
	v_mfma_f32_16x16x32_bf16 v[98:101], v[174:177], v[190:193], v[98:101]
	v_mfma_f32_16x16x32_bf16 v[90:93], v[166:169], v[206:209], v[90:93]
	v_mfma_f32_16x16x32_bf16 v[82:85], v[174:177], v[206:209], v[82:85]
	v_mfma_f32_16x16x32_bf16 v[74:77], v[166:169], v[224:227], v[74:77]
	v_mfma_f32_16x16x32_bf16 v[66:69], v[174:177], v[224:227], v[66:69]
	s_barrier
	s_add_i32 s28, s51, s36
	v_lshl_add_u64 v[140:141], v[140:141], 0, s[84:85]
	s_mov_b32 m0, s28
	ds_read_b128 v[178:181], v145 offset:49152
	ds_read_b128 v[182:185], v145 offset:50176
	ds_read_b128 v[186:189], v145 offset:51200
	ds_read_b128 v[190:193], v145 offset:52224
	ds_read_b128 v[202:205], v145 offset:53248
	ds_read_b128 v[206:209], v145 offset:54272
	ds_read_b128 v[220:223], v145 offset:55296
	ds_read_b128 v[224:227], v145 offset:56320
	global_load_lds_dwordx4 v[140:141], off
	s_add_i32 m0, s28, 0x2000
	s_add_u32 s20, s20, 0x40080
	v_lshl_add_u64 v[140:141], v[194:195], 0, s[84:85]
	s_addc_u32 s21, s21, 0
	s_add_i32 s28, s52, s36
	global_load_lds_dwordx4 v[140:141], off
	v_lshl_add_u64 v[140:141], s[20:21], 0, v[0:1]
	s_mov_b32 m0, s28
	s_nop 0
	global_load_lds_dwordx4 v[140:141], off
	v_lshl_add_u64 v[140:141], s[20:21], 0, v[130:131]
	s_add_i32 m0, s28, 0x2000
	s_nop 0
	global_load_lds_dwordx4 v[140:141], off
	v_lshl_add_u64 v[140:141], v[198:199], 0, s[84:85]
	s_mov_b32 m0, s76
	s_nop 0
	global_load_lds_dwordx4 v[140:141], off
	v_lshl_add_u64 v[140:141], v[200:201], 0, s[84:85]
	s_mov_b32 m0, s77
	s_nop 0
	global_load_lds_dwordx4 v[140:141], off
	s_waitcnt vmcnt(8)
	s_waitcnt lgkmcnt(0)
	s_barrier
	v_mfma_f32_16x16x32_bf16 v[62:65], v[146:149], v[178:181], v[62:65]
	v_mfma_f32_16x16x32_bf16 v[54:57], v[154:157], v[178:181], v[54:57]
	v_mfma_f32_16x16x32_bf16 v[46:49], v[146:149], v[186:189], v[46:49]
	v_mfma_f32_16x16x32_bf16 v[38:41], v[154:157], v[186:189], v[38:41]
	v_mfma_f32_16x16x32_bf16 v[30:33], v[146:149], v[202:205], v[30:33]
	v_mfma_f32_16x16x32_bf16 v[22:25], v[154:157], v[202:205], v[22:25]
	v_mfma_f32_16x16x32_bf16 v[14:17], v[146:149], v[220:223], v[14:17]
	v_mfma_f32_16x16x32_bf16 v[6:9], v[154:157], v[220:223], v[6:9]
	v_mfma_f32_16x16x32_bf16 v[62:65], v[150:153], v[182:185], v[62:65]
	v_mfma_f32_16x16x32_bf16 v[54:57], v[158:161], v[182:185], v[54:57]
	v_mfma_f32_16x16x32_bf16 v[46:49], v[150:153], v[190:193], v[46:49]
	v_mfma_f32_16x16x32_bf16 v[38:41], v[158:161], v[190:193], v[38:41]
	v_mfma_f32_16x16x32_bf16 v[30:33], v[150:153], v[206:209], v[30:33]
	v_mfma_f32_16x16x32_bf16 v[22:25], v[158:161], v[206:209], v[22:25]
	v_mfma_f32_16x16x32_bf16 v[14:17], v[150:153], v[224:227], v[14:17]
	v_mfma_f32_16x16x32_bf16 v[6:9], v[158:161], v[224:227], v[6:9]
	v_mfma_f32_16x16x32_bf16 v[58:61], v[162:165], v[178:181], v[58:61]
	v_mfma_f32_16x16x32_bf16 v[50:53], v[170:173], v[178:181], v[50:53]
	v_mfma_f32_16x16x32_bf16 v[42:45], v[162:165], v[186:189], v[42:45]
	v_mfma_f32_16x16x32_bf16 v[34:37], v[170:173], v[186:189], v[34:37]
	v_mfma_f32_16x16x32_bf16 v[26:29], v[162:165], v[202:205], v[26:29]
	v_mfma_f32_16x16x32_bf16 v[18:21], v[170:173], v[202:205], v[18:21]
	v_mfma_f32_16x16x32_bf16 v[10:13], v[162:165], v[220:223], v[10:13]
	v_mfma_f32_16x16x32_bf16 v[2:5], v[170:173], v[220:223], v[2:5]
	v_mfma_f32_16x16x32_bf16 v[58:61], v[166:169], v[182:185], v[58:61]
	v_mfma_f32_16x16x32_bf16 v[50:53], v[174:177], v[182:185], v[50:53]
	v_mfma_f32_16x16x32_bf16 v[42:45], v[166:169], v[190:193], v[42:45]
	v_mfma_f32_16x16x32_bf16 v[34:37], v[174:177], v[190:193], v[34:37]
	v_mfma_f32_16x16x32_bf16 v[26:29], v[166:169], v[206:209], v[26:29]
	v_mfma_f32_16x16x32_bf16 v[18:21], v[174:177], v[206:209], v[18:21]
	v_mfma_f32_16x16x32_bf16 v[10:13], v[166:169], v[224:227], v[10:13]
	v_mfma_f32_16x16x32_bf16 v[2:5], v[174:177], v[224:227], v[2:5]
	s_barrier
	s_add_i32 s50, s50, 2
	s_add_u32 s4, s4, 0x100
	s_addc_u32 s5, s5, 0
	s_add_u32 s48, s48, 0x100
	s_addc_u32 s49, s49, 0
	s_cmp_gt_u32 s50, 13
	s_cbranch_scc0 .LBB0_692
